# weight transposes: 32 loads in flight per wave; bias_gemv wave sums via DPP and v_readlane
# speedup vs baseline: 1.0109x; 1.0084x over previous
.LBB0_60:
	s_lshl_b32 s16, s4, 1
	s_lshl_b32 s17, s5, 1
	v_or_b32_e32 v50, s16, v1
	v_or_b32_e32 v51, s17, v0
	s_add_i32 s18, s16, 4
	s_add_i32 s19, s17, 4
	s_add_i32 s20, s16, 8
	s_add_i32 s21, s17, 8
	s_add_i32 s22, s16, 12
	s_add_i32 s23, s17, 12
	s_add_i32 s24, s16, 16
	s_add_i32 s25, s17, 16
	s_add_i32 s26, s16, 20
	s_add_i32 s27, s17, 20
	s_add_i32 s28, s16, 24
	s_add_i32 s29, s17, 24
	s_add_i32 s16, s16, 28
	s_add_i32 s17, s17, 28
	v_add_u32_e32 v18, s2, v51
	v_or_b32_e32 v52, s18, v1
	v_or_b32_e32 v53, s19, v0
	v_or_b32_e32 v54, s20, v1
	v_or_b32_e32 v55, s21, v0
	v_or_b32_e32 v56, s22, v1
	v_or_b32_e32 v57, s23, v0
	v_or_b32_e32 v58, s24, v1
	v_or_b32_e32 v59, s25, v0
	v_or_b32_e32 v60, s26, v1
	v_or_b32_e32 v61, s27, v0
	v_or_b32_e32 v62, s28, v1
	v_or_b32_e32 v63, s29, v0
	v_or_b32_e32 v64, s16, v1
	v_or_b32_e32 v65, s17, v0
	v_add_u32_e32 v20, s3, v50
	v_mad_i64_i32 v[18:19], s[16:17], v18, s9, v[12:13]
	v_add_u32_e32 v24, s3, v52
	v_add_u32_e32 v22, s2, v53
	v_add_u32_e32 v28, s3, v54
	v_add_u32_e32 v26, s2, v55
	v_add_u32_e32 v32, s3, v56
	v_add_u32_e32 v30, s2, v57
	v_add_u32_e32 v36, s3, v58
	v_add_u32_e32 v34, s2, v59
	v_add_u32_e32 v40, s3, v60
	v_add_u32_e32 v38, s2, v61
	v_add_u32_e32 v44, s3, v62
	v_add_u32_e32 v42, s2, v63
	v_add_u32_e32 v48, s3, v64
	v_add_u32_e32 v46, s2, v65
	v_mad_i64_i32 v[20:21], s[16:17], v20, s9, v[12:13]
	v_mad_i64_i32 v[22:23], s[16:17], v22, s9, v[12:13]
	v_mad_i64_i32 v[24:25], s[16:17], v24, s9, v[12:13]
	v_mad_i64_i32 v[26:27], s[16:17], v26, s9, v[12:13]
	v_mad_i64_i32 v[28:29], s[16:17], v28, s9, v[12:13]
	v_mad_i64_i32 v[30:31], s[16:17], v30, s9, v[12:13]
	v_mad_i64_i32 v[32:33], s[16:17], v32, s9, v[12:13]
	v_mad_i64_i32 v[34:35], s[16:17], v34, s9, v[12:13]
	v_mad_i64_i32 v[36:37], s[16:17], v36, s9, v[12:13]
	v_mad_i64_i32 v[38:39], s[16:17], v38, s9, v[12:13]
	v_mad_i64_i32 v[40:41], s[16:17], v40, s9, v[12:13]
	v_mad_i64_i32 v[42:43], s[16:17], v42, s9, v[12:13]
	v_mad_i64_i32 v[44:45], s[16:17], v44, s9, v[12:13]
	v_mad_i64_i32 v[46:47], s[16:17], v46, s9, v[12:13]
	v_mad_i64_i32 v[48:49], s[16:17], v48, s9, v[12:13]
	global_load_dword v66, v[18:19], off
	global_load_dword v67, v[20:21], off
	global_load_dword v68, v[22:23], off
	global_load_dword v69, v[24:25], off
	global_load_dword v70, v[26:27], off
	global_load_dword v71, v[28:29], off
	global_load_dword v72, v[30:31], off
	global_load_dword v73, v[32:33], off
	global_load_dword v74, v[34:35], off
	global_load_dword v75, v[36:37], off
	global_load_dword v76, v[38:39], off
	global_load_dword v77, v[40:41], off
	global_load_dword v78, v[42:43], off
	global_load_dword v79, v[44:45], off
	global_load_dword v80, v[46:47], off
	global_load_dword v81, v[48:49], off
	s_add_i32 s5, s5, 16
	s_add_i32 s4, s4, 16
	s_lshl_b32 s16, s4, 1
	s_lshl_b32 s17, s5, 1
	v_or_b32_e32 v132, s16, v1
	v_or_b32_e32 v133, s17, v0
	s_add_i32 s18, s16, 4
	s_add_i32 s19, s17, 4
	s_add_i32 s20, s16, 8
	s_add_i32 s21, s17, 8
	s_add_i32 s22, s16, 12
	s_add_i32 s23, s17, 12
	s_add_i32 s24, s16, 16
	s_add_i32 s25, s17, 16
	s_add_i32 s26, s16, 20
	s_add_i32 s27, s17, 20
	s_add_i32 s28, s16, 24
	s_add_i32 s29, s17, 24
	s_add_i32 s16, s16, 28
	s_add_i32 s17, s17, 28
	v_add_u32_e32 v100, s2, v133
	v_or_b32_e32 v134, s18, v1
	v_or_b32_e32 v135, s19, v0
	v_or_b32_e32 v136, s20, v1
	v_or_b32_e32 v137, s21, v0
	v_or_b32_e32 v138, s22, v1
	v_or_b32_e32 v139, s23, v0
	v_or_b32_e32 v140, s24, v1
	v_or_b32_e32 v141, s25, v0
	v_or_b32_e32 v142, s26, v1
	v_or_b32_e32 v143, s27, v0
	v_or_b32_e32 v144, s28, v1
	v_or_b32_e32 v145, s29, v0
	v_or_b32_e32 v146, s16, v1
	v_or_b32_e32 v147, s17, v0
	v_add_u32_e32 v102, s3, v132
	v_mad_i64_i32 v[100:101], s[16:17], v100, s9, v[12:13]
	v_add_u32_e32 v106, s3, v134
	v_add_u32_e32 v104, s2, v135
	v_add_u32_e32 v110, s3, v136
	v_add_u32_e32 v108, s2, v137
	v_add_u32_e32 v114, s3, v138
	v_add_u32_e32 v112, s2, v139
	v_add_u32_e32 v118, s3, v140
	v_add_u32_e32 v116, s2, v141
	v_add_u32_e32 v122, s3, v142
	v_add_u32_e32 v120, s2, v143
	v_add_u32_e32 v126, s3, v144
	v_add_u32_e32 v124, s2, v145
	v_add_u32_e32 v130, s3, v146
	v_add_u32_e32 v128, s2, v147
	v_mad_i64_i32 v[102:103], s[16:17], v102, s9, v[12:13]
	v_mad_i64_i32 v[104:105], s[16:17], v104, s9, v[12:13]
	v_mad_i64_i32 v[106:107], s[16:17], v106, s9, v[12:13]
	v_mad_i64_i32 v[108:109], s[16:17], v108, s9, v[12:13]
	v_mad_i64_i32 v[110:111], s[16:17], v110, s9, v[12:13]
	v_mad_i64_i32 v[112:113], s[16:17], v112, s9, v[12:13]
	v_mad_i64_i32 v[114:115], s[16:17], v114, s9, v[12:13]
	v_mad_i64_i32 v[116:117], s[16:17], v116, s9, v[12:13]
	v_mad_i64_i32 v[118:119], s[16:17], v118, s9, v[12:13]
	v_mad_i64_i32 v[120:121], s[16:17], v120, s9, v[12:13]
	v_mad_i64_i32 v[122:123], s[16:17], v122, s9, v[12:13]
	v_mad_i64_i32 v[124:125], s[16:17], v124, s9, v[12:13]
	v_mad_i64_i32 v[126:127], s[16:17], v126, s9, v[12:13]
	v_mad_i64_i32 v[128:129], s[16:17], v128, s9, v[12:13]
	v_mad_i64_i32 v[130:131], s[16:17], v130, s9, v[12:13]
	global_load_dword v148, v[100:101], off
	global_load_dword v149, v[102:103], off
	global_load_dword v150, v[104:105], off
	global_load_dword v151, v[106:107], off
	global_load_dword v152, v[108:109], off
	global_load_dword v153, v[110:111], off
	global_load_dword v154, v[112:113], off
	global_load_dword v155, v[114:115], off
	global_load_dword v156, v[116:117], off
	global_load_dword v157, v[118:119], off
	global_load_dword v158, v[120:121], off
	global_load_dword v159, v[122:123], off
	global_load_dword v160, v[124:125], off
	global_load_dword v161, v[126:127], off
	global_load_dword v162, v[128:129], off
	global_load_dword v163, v[130:131], off
	v_mad_u64_u32 v[18:19], s[16:17], v51, s8, v[4:5]
	v_mad_u64_u32 v[20:21], s[16:17], v50, s8, v[4:5]
	v_mad_u64_u32 v[22:23], s[16:17], v53, s8, v[4:5]
	v_mad_u64_u32 v[24:25], s[16:17], v52, s8, v[4:5]
	v_mad_u64_u32 v[26:27], s[16:17], v55, s8, v[4:5]
	v_mad_u64_u32 v[28:29], s[16:17], v54, s8, v[4:5]
	v_mad_u64_u32 v[30:31], s[16:17], v57, s8, v[4:5]
	v_mad_u64_u32 v[32:33], s[16:17], v56, s8, v[4:5]
	v_mad_u64_u32 v[34:35], s[16:17], v59, s8, v[4:5]
	v_mad_u64_u32 v[36:37], s[16:17], v58, s8, v[4:5]
	v_mad_u64_u32 v[38:39], s[16:17], v61, s8, v[4:5]
	v_mad_u64_u32 v[40:41], s[16:17], v60, s8, v[4:5]
	v_mad_u64_u32 v[42:43], s[16:17], v63, s8, v[4:5]
	v_mad_u64_u32 v[44:45], s[16:17], v62, s8, v[4:5]
	v_mad_u64_u32 v[46:47], s[16:17], v65, s8, v[4:5]
	v_mad_u64_u32 v[48:49], s[16:17], v64, s8, v[4:5]
	s_waitcnt vmcnt(31)
	ds_write_b32 v18, v66
	s_waitcnt vmcnt(30)
	ds_write_b32 v20, v67
	s_waitcnt vmcnt(29)
	ds_write_b32 v22, v68
	s_waitcnt vmcnt(28)
	ds_write_b32 v24, v69
	s_waitcnt vmcnt(27)
	ds_write_b32 v26, v70
	s_waitcnt vmcnt(26)
	ds_write_b32 v28, v71
	s_waitcnt vmcnt(25)
	ds_write_b32 v30, v72
	s_waitcnt vmcnt(24)
	ds_write_b32 v32, v73
	s_waitcnt vmcnt(23)
	ds_write_b32 v34, v74
	s_waitcnt vmcnt(22)
	ds_write_b32 v36, v75
	s_waitcnt vmcnt(21)
	ds_write_b32 v38, v76
	s_waitcnt vmcnt(20)
	ds_write_b32 v40, v77
	s_waitcnt vmcnt(19)
	ds_write_b32 v42, v78
	s_waitcnt vmcnt(18)
	ds_write_b32 v44, v79
	s_waitcnt vmcnt(17)
	ds_write_b32 v46, v80
	s_waitcnt vmcnt(16)
	ds_write_b32 v48, v81
	v_mad_u64_u32 v[100:101], s[16:17], v133, s8, v[4:5]
	v_mad_u64_u32 v[102:103], s[16:17], v132, s8, v[4:5]
	v_mad_u64_u32 v[104:105], s[16:17], v135, s8, v[4:5]
	v_mad_u64_u32 v[106:107], s[16:17], v134, s8, v[4:5]
	v_mad_u64_u32 v[108:109], s[16:17], v137, s8, v[4:5]
	v_mad_u64_u32 v[110:111], s[16:17], v136, s8, v[4:5]
	v_mad_u64_u32 v[112:113], s[16:17], v139, s8, v[4:5]
	v_mad_u64_u32 v[114:115], s[16:17], v138, s8, v[4:5]
	v_mad_u64_u32 v[116:117], s[16:17], v141, s8, v[4:5]
	v_mad_u64_u32 v[118:119], s[16:17], v140, s8, v[4:5]
	v_mad_u64_u32 v[120:121], s[16:17], v143, s8, v[4:5]
	v_mad_u64_u32 v[122:123], s[16:17], v142, s8, v[4:5]
	v_mad_u64_u32 v[124:125], s[16:17], v145, s8, v[4:5]
	v_mad_u64_u32 v[126:127], s[16:17], v144, s8, v[4:5]
	v_mad_u64_u32 v[128:129], s[16:17], v147, s8, v[4:5]
	v_mad_u64_u32 v[130:131], s[16:17], v146, s8, v[4:5]
	s_waitcnt vmcnt(15)
	ds_write_b32 v100, v148
	s_waitcnt vmcnt(14)
	ds_write_b32 v102, v149
	s_waitcnt vmcnt(13)
	ds_write_b32 v104, v150
	s_waitcnt vmcnt(12)
	ds_write_b32 v106, v151
	s_waitcnt vmcnt(11)
	ds_write_b32 v108, v152
	s_waitcnt vmcnt(10)
	ds_write_b32 v110, v153
	s_waitcnt vmcnt(9)
	ds_write_b32 v112, v154
	s_waitcnt vmcnt(8)
	ds_write_b32 v114, v155
	s_waitcnt vmcnt(7)
	ds_write_b32 v116, v156
	s_waitcnt vmcnt(6)
	ds_write_b32 v118, v157
	s_waitcnt vmcnt(5)
	ds_write_b32 v120, v158
	s_waitcnt vmcnt(4)
	ds_write_b32 v122, v159
	s_waitcnt vmcnt(3)
	ds_write_b32 v124, v160
	s_waitcnt vmcnt(2)
	ds_write_b32 v126, v161
	s_waitcnt vmcnt(1)
	ds_write_b32 v128, v162
	s_waitcnt vmcnt(0)
	ds_write_b32 v130, v163
	s_add_i32 s5, s5, 16
	s_add_i32 s4, s4, 16
	s_add_i32 s13, s13, -16
	s_add_i32 s13, s13, -16
	s_cmp_lg_u32 s13, 0
	s_waitcnt lgkmcnt(0)
	ds_read2_b32 v[12:13], v14 offset1:33
	s_waitcnt lgkmcnt(0)
	v_cvt_pk_bf16_f32 v18, v12, v13
	ds_read2_b32 v[12:13], v14 offset0:66 offset1:99
	v_add_u32_e32 v22, s12, v5
	s_waitcnt lgkmcnt(0)
	v_cvt_pk_bf16_f32 v19, v12, v13
	ds_read2_b32 v[12:13], v14 offset0:132 offset1:165
	s_ashr_i32 s3, s2, 31
	v_ashrrev_i32_e32 v23, 31, v22
	s_waitcnt lgkmcnt(0)
	v_cvt_pk_bf16_f32 v20, v12, v13
	ds_read2_b32 v[12:13], v14 offset0:198 offset1:231
	v_lshl_add_u64 v[24:25], s[2:3], 1, v[6:7]
	v_lshlrev_b64 v[22:23], 12, v[22:23]
	s_waitcnt lgkmcnt(0)
	v_cvt_pk_bf16_f32 v21, v12, v13
	ds_read2_b32 v[12:13], v14 offset0:8 offset1:41
	v_lshl_add_u64 v[22:23], v[24:25], 0, v[22:23]
	global_store_dwordx4 v[22:23], v[18:21], off
	v_add_u32_e32 v22, s12, v15
	v_ashrrev_i32_e32 v23, 31, v22
	s_waitcnt lgkmcnt(0)
	v_cvt_pk_bf16_f32 v18, v12, v13
	ds_read2_b32 v[12:13], v14 offset0:74 offset1:107
	s_waitcnt lgkmcnt(0)
	v_cvt_pk_bf16_f32 v19, v12, v13
	ds_read2_b32 v[12:13], v14 offset0:140 offset1:173
	s_waitcnt lgkmcnt(0)
	v_cvt_pk_bf16_f32 v20, v12, v13
	ds_read2_b32 v[12:13], v14 offset0:206 offset1:239
	v_lshlrev_b64 v[22:23], 12, v[22:23]
	s_waitcnt lgkmcnt(0)
	v_cvt_pk_bf16_f32 v21, v12, v13
	ds_read2_b32 v[12:13], v14 offset0:16 offset1:49
	v_lshl_add_u64 v[22:23], v[24:25], 0, v[22:23]
	global_store_dwordx4 v[22:23], v[18:21], off
	v_add_u32_e32 v22, s12, v16
	v_ashrrev_i32_e32 v23, 31, v22
	s_waitcnt lgkmcnt(0)
	v_cvt_pk_bf16_f32 v18, v12, v13
	ds_read2_b32 v[12:13], v14 offset0:82 offset1:115
	s_waitcnt lgkmcnt(0)
	v_cvt_pk_bf16_f32 v19, v12, v13
	ds_read2_b32 v[12:13], v14 offset0:148 offset1:181
	s_waitcnt lgkmcnt(0)
	v_cvt_pk_bf16_f32 v20, v12, v13
	ds_read2_b32 v[12:13], v14 offset0:214 offset1:247
	v_lshlrev_b64 v[22:23], 12, v[22:23]
	s_waitcnt lgkmcnt(0)
	v_cvt_pk_bf16_f32 v21, v12, v13
	ds_read2_b32 v[12:13], v14 offset0:24 offset1:57
	v_lshl_add_u64 v[22:23], v[24:25], 0, v[22:23]
	global_store_dwordx4 v[22:23], v[18:21], off
	v_add_u32_e32 v22, s12, v17
	v_ashrrev_i32_e32 v23, 31, v22
	s_waitcnt lgkmcnt(0)
	v_cvt_pk_bf16_f32 v18, v12, v13
	ds_read2_b32 v[12:13], v14 offset0:90 offset1:123
	s_waitcnt lgkmcnt(0)
	v_cvt_pk_bf16_f32 v19, v12, v13
	ds_read2_b32 v[12:13], v14 offset0:156 offset1:189
	s_waitcnt lgkmcnt(0)
	v_cvt_pk_bf16_f32 v20, v12, v13
	ds_read2_b32 v[12:13], v14 offset0:222 offset1:255
	v_lshlrev_b64 v[22:23], 12, v[22:23]
	s_waitcnt lgkmcnt(0)
	v_cvt_pk_bf16_f32 v21, v12, v13
	v_lshl_add_u64 v[12:13], v[24:25], 0, v[22:23]
	global_store_dwordx4 v[12:13], v[18:21], off
	s_waitcnt lgkmcnt(0)
	s_mov_b64 s[2:3], 0

.LBB0_66:
	s_lshl_b32 s12, s3, 1
	s_lshl_b32 s13, s4, 1
	v_or_b32_e32 v50, s12, v1
	v_or_b32_e32 v51, s13, v0
	s_add_i32 s16, s12, 4
	s_add_i32 s17, s13, 4
	s_add_i32 s18, s12, 8
	s_add_i32 s19, s13, 8
	s_add_i32 s20, s12, 12
	s_add_i32 s21, s13, 12
	s_add_i32 s22, s12, 16
	s_add_i32 s23, s13, 16
	s_add_i32 s24, s12, 20
	s_add_i32 s25, s13, 20
	s_add_i32 s26, s12, 24
	s_add_i32 s27, s13, 24
	s_add_i32 s12, s12, 28
	s_add_i32 s13, s13, 28
	v_add_u32_e32 v20, s2, v51
	v_or_b32_e32 v52, s16, v1
	v_or_b32_e32 v53, s17, v0
	v_or_b32_e32 v54, s18, v1
	v_or_b32_e32 v55, s19, v0
	v_or_b32_e32 v56, s20, v1
	v_or_b32_e32 v57, s21, v0
	v_or_b32_e32 v58, s22, v1
	v_or_b32_e32 v59, s23, v0
	v_or_b32_e32 v60, s24, v1
	v_or_b32_e32 v61, s25, v0
	v_or_b32_e32 v62, s26, v1
	v_or_b32_e32 v63, s27, v0
	v_or_b32_e32 v64, s12, v1
	v_or_b32_e32 v65, s13, v0
	v_add_u32_e32 v18, s1, v50
	v_ashrrev_i32_e32 v21, 31, v20
	v_add_u32_e32 v22, s1, v52
	v_add_u32_e32 v24, s2, v53
	v_add_u32_e32 v26, s1, v54
	v_add_u32_e32 v28, s2, v55
	v_add_u32_e32 v30, s1, v56
	v_add_u32_e32 v32, s2, v57
	v_add_u32_e32 v34, s1, v58
	v_add_u32_e32 v36, s2, v59
	v_add_u32_e32 v38, s1, v60
	v_add_u32_e32 v40, s2, v61
	v_add_u32_e32 v42, s1, v62
	v_add_u32_e32 v44, s2, v63
	v_add_u32_e32 v46, s1, v64
	v_add_u32_e32 v48, s2, v65
	v_ashrrev_i32_e32 v19, 31, v18
	v_lshlrev_b64 v[20:21], 13, v[20:21]
	v_ashrrev_i32_e32 v25, 31, v24
	v_ashrrev_i32_e32 v23, 31, v22
	v_ashrrev_i32_e32 v29, 31, v28
	v_ashrrev_i32_e32 v27, 31, v26
	v_ashrrev_i32_e32 v33, 31, v32
	v_ashrrev_i32_e32 v31, 31, v30
	v_ashrrev_i32_e32 v37, 31, v36
	v_ashrrev_i32_e32 v35, 31, v34
	v_ashrrev_i32_e32 v41, 31, v40
	v_ashrrev_i32_e32 v39, 31, v38
	v_ashrrev_i32_e32 v45, 31, v44
	v_ashrrev_i32_e32 v43, 31, v42
	v_ashrrev_i32_e32 v49, 31, v48
	v_ashrrev_i32_e32 v47, 31, v46
	v_lshlrev_b64 v[18:19], 13, v[18:19]
	v_lshl_add_u64 v[20:21], v[12:13], 0, v[20:21]
	v_lshlrev_b64 v[22:23], 13, v[22:23]
	v_lshlrev_b64 v[24:25], 13, v[24:25]
	v_lshlrev_b64 v[26:27], 13, v[26:27]
	v_lshlrev_b64 v[28:29], 13, v[28:29]
	v_lshlrev_b64 v[30:31], 13, v[30:31]
	v_lshlrev_b64 v[32:33], 13, v[32:33]
	v_lshlrev_b64 v[34:35], 13, v[34:35]
	v_lshlrev_b64 v[36:37], 13, v[36:37]
	v_lshlrev_b64 v[38:39], 13, v[38:39]
	v_lshlrev_b64 v[40:41], 13, v[40:41]
	v_lshlrev_b64 v[42:43], 13, v[42:43]
	v_lshlrev_b64 v[44:45], 13, v[44:45]
	v_lshlrev_b64 v[46:47], 13, v[46:47]
	v_lshlrev_b64 v[48:49], 13, v[48:49]
	v_lshl_add_u64 v[18:19], v[12:13], 0, v[18:19]
	v_lshl_add_u64 v[24:25], v[12:13], 0, v[24:25]
	v_lshl_add_u64 v[22:23], v[12:13], 0, v[22:23]
	v_lshl_add_u64 v[28:29], v[12:13], 0, v[28:29]
	v_lshl_add_u64 v[26:27], v[12:13], 0, v[26:27]
	v_lshl_add_u64 v[32:33], v[12:13], 0, v[32:33]
	v_lshl_add_u64 v[30:31], v[12:13], 0, v[30:31]
	v_lshl_add_u64 v[36:37], v[12:13], 0, v[36:37]
	v_lshl_add_u64 v[34:35], v[12:13], 0, v[34:35]
	v_lshl_add_u64 v[40:41], v[12:13], 0, v[40:41]
	v_lshl_add_u64 v[38:39], v[12:13], 0, v[38:39]
	v_lshl_add_u64 v[44:45], v[12:13], 0, v[44:45]
	v_lshl_add_u64 v[42:43], v[12:13], 0, v[42:43]
	v_lshl_add_u64 v[48:49], v[12:13], 0, v[48:49]
	v_lshl_add_u64 v[46:47], v[12:13], 0, v[46:47]
	global_load_dword v66, v[20:21], off
	global_load_dword v67, v[18:19], off
	global_load_dword v68, v[24:25], off
	global_load_dword v69, v[22:23], off
	global_load_dword v70, v[28:29], off
	global_load_dword v71, v[26:27], off
	global_load_dword v72, v[32:33], off
	global_load_dword v73, v[30:31], off
	global_load_dword v74, v[36:37], off
	global_load_dword v75, v[34:35], off
	global_load_dword v76, v[40:41], off
	global_load_dword v77, v[38:39], off
	global_load_dword v78, v[44:45], off
	global_load_dword v79, v[42:43], off
	global_load_dword v80, v[48:49], off
	global_load_dword v81, v[46:47], off
	s_add_i32 s4, s4, 16
	s_add_i32 s3, s3, 16
	s_lshl_b32 s12, s3, 1
	s_lshl_b32 s13, s4, 1
	v_or_b32_e32 v132, s12, v1
	v_or_b32_e32 v133, s13, v0
	s_add_i32 s16, s12, 4
	s_add_i32 s17, s13, 4
	s_add_i32 s18, s12, 8
	s_add_i32 s19, s13, 8
	s_add_i32 s20, s12, 12
	s_add_i32 s21, s13, 12
	s_add_i32 s22, s12, 16
	s_add_i32 s23, s13, 16
	s_add_i32 s24, s12, 20
	s_add_i32 s25, s13, 20
	s_add_i32 s26, s12, 24
	s_add_i32 s27, s13, 24
	s_add_i32 s12, s12, 28
	s_add_i32 s13, s13, 28
	v_add_u32_e32 v102, s2, v133
	v_or_b32_e32 v134, s16, v1
	v_or_b32_e32 v135, s17, v0
	v_or_b32_e32 v136, s18, v1
	v_or_b32_e32 v137, s19, v0
	v_or_b32_e32 v138, s20, v1
	v_or_b32_e32 v139, s21, v0
	v_or_b32_e32 v140, s22, v1
	v_or_b32_e32 v141, s23, v0
	v_or_b32_e32 v142, s24, v1
	v_or_b32_e32 v143, s25, v0
	v_or_b32_e32 v144, s26, v1
	v_or_b32_e32 v145, s27, v0
	v_or_b32_e32 v146, s12, v1
	v_or_b32_e32 v147, s13, v0
	v_add_u32_e32 v100, s1, v132
	v_ashrrev_i32_e32 v103, 31, v102
	v_add_u32_e32 v104, s1, v134
	v_add_u32_e32 v106, s2, v135
	v_add_u32_e32 v108, s1, v136
	v_add_u32_e32 v110, s2, v137
	v_add_u32_e32 v112, s1, v138
	v_add_u32_e32 v114, s2, v139
	v_add_u32_e32 v116, s1, v140
	v_add_u32_e32 v118, s2, v141
	v_add_u32_e32 v120, s1, v142
	v_add_u32_e32 v122, s2, v143
	v_add_u32_e32 v124, s1, v144
	v_add_u32_e32 v126, s2, v145
	v_add_u32_e32 v128, s1, v146
	v_add_u32_e32 v130, s2, v147
	v_ashrrev_i32_e32 v101, 31, v100
	v_lshlrev_b64 v[102:103], 13, v[102:103]
	v_ashrrev_i32_e32 v107, 31, v106
	v_ashrrev_i32_e32 v105, 31, v104
	v_ashrrev_i32_e32 v111, 31, v110
	v_ashrrev_i32_e32 v109, 31, v108
	v_ashrrev_i32_e32 v115, 31, v114
	v_ashrrev_i32_e32 v113, 31, v112
	v_ashrrev_i32_e32 v119, 31, v118
	v_ashrrev_i32_e32 v117, 31, v116
	v_ashrrev_i32_e32 v123, 31, v122
	v_ashrrev_i32_e32 v121, 31, v120
	v_ashrrev_i32_e32 v127, 31, v126
	v_ashrrev_i32_e32 v125, 31, v124
	v_ashrrev_i32_e32 v131, 31, v130
	v_ashrrev_i32_e32 v129, 31, v128
	v_lshlrev_b64 v[100:101], 13, v[100:101]
	v_lshl_add_u64 v[102:103], v[12:13], 0, v[102:103]
	v_lshlrev_b64 v[104:105], 13, v[104:105]
	v_lshlrev_b64 v[106:107], 13, v[106:107]
	v_lshlrev_b64 v[108:109], 13, v[108:109]
	v_lshlrev_b64 v[110:111], 13, v[110:111]
	v_lshlrev_b64 v[112:113], 13, v[112:113]
	v_lshlrev_b64 v[114:115], 13, v[114:115]
	v_lshlrev_b64 v[116:117], 13, v[116:117]
	v_lshlrev_b64 v[118:119], 13, v[118:119]
	v_lshlrev_b64 v[120:121], 13, v[120:121]
	v_lshlrev_b64 v[122:123], 13, v[122:123]
	v_lshlrev_b64 v[124:125], 13, v[124:125]
	v_lshlrev_b64 v[126:127], 13, v[126:127]
	v_lshlrev_b64 v[128:129], 13, v[128:129]
	v_lshlrev_b64 v[130:131], 13, v[130:131]
	v_lshl_add_u64 v[100:101], v[12:13], 0, v[100:101]
	v_lshl_add_u64 v[106:107], v[12:13], 0, v[106:107]
	v_lshl_add_u64 v[104:105], v[12:13], 0, v[104:105]
	v_lshl_add_u64 v[110:111], v[12:13], 0, v[110:111]
	v_lshl_add_u64 v[108:109], v[12:13], 0, v[108:109]
	v_lshl_add_u64 v[114:115], v[12:13], 0, v[114:115]
	v_lshl_add_u64 v[112:113], v[12:13], 0, v[112:113]
	v_lshl_add_u64 v[118:119], v[12:13], 0, v[118:119]
	v_lshl_add_u64 v[116:117], v[12:13], 0, v[116:117]
	v_lshl_add_u64 v[122:123], v[12:13], 0, v[122:123]
	v_lshl_add_u64 v[120:121], v[12:13], 0, v[120:121]
	v_lshl_add_u64 v[126:127], v[12:13], 0, v[126:127]
	v_lshl_add_u64 v[124:125], v[12:13], 0, v[124:125]
	v_lshl_add_u64 v[130:131], v[12:13], 0, v[130:131]
	v_lshl_add_u64 v[128:129], v[12:13], 0, v[128:129]
	global_load_dword v148, v[102:103], off
	global_load_dword v149, v[100:101], off
	global_load_dword v150, v[106:107], off
	global_load_dword v151, v[104:105], off
	global_load_dword v152, v[110:111], off
	global_load_dword v153, v[108:109], off
	global_load_dword v154, v[114:115], off
	global_load_dword v155, v[112:113], off
	global_load_dword v156, v[118:119], off
	global_load_dword v157, v[116:117], off
	global_load_dword v158, v[122:123], off
	global_load_dword v159, v[120:121], off
	global_load_dword v160, v[126:127], off
	global_load_dword v161, v[124:125], off
	global_load_dword v162, v[130:131], off
	global_load_dword v163, v[128:129], off
	v_mad_u64_u32 v[18:19], s[12:13], v51, s8, v[4:5]
	v_mad_u64_u32 v[20:21], s[12:13], v50, s8, v[4:5]
	v_mad_u64_u32 v[22:23], s[12:13], v53, s8, v[4:5]
	v_mad_u64_u32 v[24:25], s[12:13], v52, s8, v[4:5]
	v_mad_u64_u32 v[26:27], s[12:13], v55, s8, v[4:5]
	v_mad_u64_u32 v[28:29], s[12:13], v54, s8, v[4:5]
	v_mad_u64_u32 v[30:31], s[12:13], v57, s8, v[4:5]
	v_mad_u64_u32 v[32:33], s[12:13], v56, s8, v[4:5]
	v_mad_u64_u32 v[34:35], s[12:13], v59, s8, v[4:5]
	v_mad_u64_u32 v[36:37], s[12:13], v58, s8, v[4:5]
	v_mad_u64_u32 v[38:39], s[12:13], v61, s8, v[4:5]
	v_mad_u64_u32 v[40:41], s[12:13], v60, s8, v[4:5]
	v_mad_u64_u32 v[42:43], s[12:13], v63, s8, v[4:5]
	v_mad_u64_u32 v[44:45], s[12:13], v62, s8, v[4:5]
	v_mad_u64_u32 v[46:47], s[12:13], v65, s8, v[4:5]
	v_mad_u64_u32 v[48:49], s[12:13], v64, s8, v[4:5]
	s_waitcnt vmcnt(31)
	ds_write_b32 v18, v66
	s_waitcnt vmcnt(30)
	ds_write_b32 v20, v67
	s_waitcnt vmcnt(29)
	ds_write_b32 v22, v68
	s_waitcnt vmcnt(28)
	ds_write_b32 v24, v69
	s_waitcnt vmcnt(27)
	ds_write_b32 v26, v70
	s_waitcnt vmcnt(26)
	ds_write_b32 v28, v71
	s_waitcnt vmcnt(25)
	ds_write_b32 v30, v72
	s_waitcnt vmcnt(24)
	ds_write_b32 v32, v73
	s_waitcnt vmcnt(23)
	ds_write_b32 v34, v74
	s_waitcnt vmcnt(22)
	ds_write_b32 v36, v75
	s_waitcnt vmcnt(21)
	ds_write_b32 v38, v76
	s_waitcnt vmcnt(20)
	ds_write_b32 v40, v77
	s_waitcnt vmcnt(19)
	ds_write_b32 v42, v78
	s_waitcnt vmcnt(18)
	ds_write_b32 v44, v79
	s_waitcnt vmcnt(17)
	ds_write_b32 v46, v80
	s_waitcnt vmcnt(16)
	ds_write_b32 v48, v81
	v_mad_u64_u32 v[100:101], s[12:13], v133, s8, v[4:5]
	v_mad_u64_u32 v[102:103], s[12:13], v132, s8, v[4:5]
	v_mad_u64_u32 v[104:105], s[12:13], v135, s8, v[4:5]
	v_mad_u64_u32 v[106:107], s[12:13], v134, s8, v[4:5]
	v_mad_u64_u32 v[108:109], s[12:13], v137, s8, v[4:5]
	v_mad_u64_u32 v[110:111], s[12:13], v136, s8, v[4:5]
	v_mad_u64_u32 v[112:113], s[12:13], v139, s8, v[4:5]
	v_mad_u64_u32 v[114:115], s[12:13], v138, s8, v[4:5]
	v_mad_u64_u32 v[116:117], s[12:13], v141, s8, v[4:5]
	v_mad_u64_u32 v[118:119], s[12:13], v140, s8, v[4:5]
	v_mad_u64_u32 v[120:121], s[12:13], v143, s8, v[4:5]
	v_mad_u64_u32 v[122:123], s[12:13], v142, s8, v[4:5]
	v_mad_u64_u32 v[124:125], s[12:13], v145, s8, v[4:5]
	v_mad_u64_u32 v[126:127], s[12:13], v144, s8, v[4:5]
	v_mad_u64_u32 v[128:129], s[12:13], v147, s8, v[4:5]
	v_mad_u64_u32 v[130:131], s[12:13], v146, s8, v[4:5]
	s_waitcnt vmcnt(15)
	ds_write_b32 v100, v148
	s_waitcnt vmcnt(14)
	ds_write_b32 v102, v149
	s_waitcnt vmcnt(13)
	ds_write_b32 v104, v150
	s_waitcnt vmcnt(12)
	ds_write_b32 v106, v151
	s_waitcnt vmcnt(11)
	ds_write_b32 v108, v152
	s_waitcnt vmcnt(10)
	ds_write_b32 v110, v153
	s_waitcnt vmcnt(9)
	ds_write_b32 v112, v154
	s_waitcnt vmcnt(8)
	ds_write_b32 v114, v155
	s_waitcnt vmcnt(7)
	ds_write_b32 v116, v156
	s_waitcnt vmcnt(6)
	ds_write_b32 v118, v157
	s_waitcnt vmcnt(5)
	ds_write_b32 v120, v158
	s_waitcnt vmcnt(4)
	ds_write_b32 v122, v159
	s_waitcnt vmcnt(3)
	ds_write_b32 v124, v160
	s_waitcnt vmcnt(2)
	ds_write_b32 v126, v161
	s_waitcnt vmcnt(1)
	ds_write_b32 v128, v162
	s_waitcnt vmcnt(0)
	ds_write_b32 v130, v163
	s_add_i32 s4, s4, 16
	s_add_i32 s3, s3, 16
	s_add_i32 s5, s5, -16
	s_add_i32 s5, s5, -16
	s_cmp_lg_u32 s5, 0
	s_waitcnt lgkmcnt(0)
	ds_read2_b32 v[12:13], v14 offset1:33
	s_waitcnt lgkmcnt(0)
	v_cvt_pk_bf16_f32 v18, v12, v13
	ds_read2_b32 v[12:13], v14 offset0:66 offset1:99
	v_or_b32_e32 v24, s0, v5
	s_waitcnt lgkmcnt(0)
	v_cvt_pk_bf16_f32 v19, v12, v13
	ds_read2_b32 v[12:13], v14 offset0:132 offset1:165
	s_ashr_i32 s3, s2, 31
	v_mul_lo_u32 v24, v24, s10
	s_waitcnt lgkmcnt(0)
	v_cvt_pk_bf16_f32 v20, v12, v13
	ds_read2_b32 v[12:13], v14 offset0:198 offset1:231
	v_lshl_add_u64 v[22:23], s[2:3], 1, v[8:9]
	v_ashrrev_i32_e32 v25, 31, v24
	s_waitcnt lgkmcnt(0)
	v_cvt_pk_bf16_f32 v21, v12, v13
	ds_read2_b32 v[12:13], v14 offset0:8 offset1:41
	v_lshl_add_u64 v[24:25], v[24:25], 1, v[22:23]
	global_store_dwordx4 v[24:25], v[18:21], off
	v_or_b32_e32 v24, s0, v15
	v_mul_lo_u32 v24, v24, s10
	s_waitcnt lgkmcnt(0)
	v_cvt_pk_bf16_f32 v18, v12, v13
	ds_read2_b32 v[12:13], v14 offset0:74 offset1:107
	s_waitcnt lgkmcnt(0)
	v_cvt_pk_bf16_f32 v19, v12, v13
	ds_read2_b32 v[12:13], v14 offset0:140 offset1:173
	s_waitcnt lgkmcnt(0)
	v_cvt_pk_bf16_f32 v20, v12, v13
	ds_read2_b32 v[12:13], v14 offset0:206 offset1:239
	v_ashrrev_i32_e32 v25, 31, v24
	s_waitcnt lgkmcnt(0)
	v_cvt_pk_bf16_f32 v21, v12, v13
	ds_read2_b32 v[12:13], v14 offset0:16 offset1:49
	v_lshl_add_u64 v[24:25], v[24:25], 1, v[22:23]
	global_store_dwordx4 v[24:25], v[18:21], off
	v_or_b32_e32 v24, s0, v16
	v_mul_lo_u32 v24, v24, s10
	s_waitcnt lgkmcnt(0)
	v_cvt_pk_bf16_f32 v18, v12, v13
	ds_read2_b32 v[12:13], v14 offset0:82 offset1:115
	s_waitcnt lgkmcnt(0)
	v_cvt_pk_bf16_f32 v19, v12, v13
	ds_read2_b32 v[12:13], v14 offset0:148 offset1:181
	s_waitcnt lgkmcnt(0)
	v_cvt_pk_bf16_f32 v20, v12, v13
	ds_read2_b32 v[12:13], v14 offset0:214 offset1:247
	v_ashrrev_i32_e32 v25, 31, v24
	s_waitcnt lgkmcnt(0)
	v_cvt_pk_bf16_f32 v21, v12, v13
	ds_read2_b32 v[12:13], v14 offset0:24 offset1:57
	v_lshl_add_u64 v[24:25], v[24:25], 1, v[22:23]
	global_store_dwordx4 v[24:25], v[18:21], off
	s_waitcnt lgkmcnt(0)
	s_nop 0
	v_cvt_pk_bf16_f32 v18, v12, v13
	ds_read2_b32 v[12:13], v14 offset0:90 offset1:123
	v_or_b32_e32 v21, s0, v17
	s_waitcnt lgkmcnt(0)
	v_cvt_pk_bf16_f32 v19, v12, v13
	ds_read2_b32 v[12:13], v14 offset0:156 offset1:189
	v_mul_lo_u32 v24, v21, s10
	s_waitcnt lgkmcnt(0)
	v_cvt_pk_bf16_f32 v20, v12, v13
	ds_read2_b32 v[12:13], v14 offset0:222 offset1:255
	v_ashrrev_i32_e32 v25, 31, v24
	s_waitcnt lgkmcnt(0)
	v_cvt_pk_bf16_f32 v21, v12, v13
	v_lshl_add_u64 v[12:13], v[24:25], 1, v[22:23]
	global_store_dwordx4 v[12:13], v[18:21], off
	s_waitcnt lgkmcnt(0)
	s_branch .LBB0_53

.LBB0_341:
	s_lshl_b32 s15, s7, 1
	s_lshl_b32 s16, s11, 1
	v_or_b32_e32 v2, s15, v1
	v_or_b32_e32 v27, s16, v0
	s_add_i32 s17, s15, 4
	s_add_i32 s18, s16, 4
	s_add_i32 s19, s15, 8
	s_add_i32 s20, s16, 8
	s_add_i32 s21, s15, 12
	s_add_i32 s22, s16, 12
	s_add_i32 s23, s15, 16
	s_add_i32 s24, s16, 16
	s_add_i32 s25, s15, 20
	s_add_i32 s26, s16, 20
	s_add_i32 s27, s15, 24
	s_add_i32 s28, s16, 24
	s_add_i32 s15, s15, 28
	s_add_i32 s16, s16, 28
	v_add_u32_e32 v38, s6, v27
	v_or_b32_e32 v29, s17, v1
	v_or_b32_e32 v68, s18, v0
	v_or_b32_e32 v69, s19, v1
	v_or_b32_e32 v70, s20, v0
	v_or_b32_e32 v71, s21, v1
	v_or_b32_e32 v72, s22, v0
	v_or_b32_e32 v73, s23, v1
	v_or_b32_e32 v74, s24, v0
	v_or_b32_e32 v75, s25, v1
	v_or_b32_e32 v76, s26, v0
	v_or_b32_e32 v77, s27, v1
	v_or_b32_e32 v78, s28, v0
	v_or_b32_e32 v79, s15, v1
	v_or_b32_e32 v80, s16, v0
	v_add_u32_e32 v36, s3, v2
	v_ashrrev_i32_e32 v39, 31, v38
	v_add_u32_e32 v40, s3, v29
	v_add_u32_e32 v42, s6, v68
	v_add_u32_e32 v44, s3, v69
	v_add_u32_e32 v46, s6, v70
	v_add_u32_e32 v48, s3, v71
	v_add_u32_e32 v50, s6, v72
	v_add_u32_e32 v52, s3, v73
	v_add_u32_e32 v54, s6, v74
	v_add_u32_e32 v56, s3, v75
	v_add_u32_e32 v58, s6, v76
	v_add_u32_e32 v60, s3, v77
	v_add_u32_e32 v62, s6, v78
	v_add_u32_e32 v64, s3, v79
	v_add_u32_e32 v66, s6, v80
	v_ashrrev_i32_e32 v37, 31, v36
	v_lshlrev_b64 v[38:39], 15, v[38:39]
	v_ashrrev_i32_e32 v43, 31, v42
	v_ashrrev_i32_e32 v41, 31, v40
	v_ashrrev_i32_e32 v47, 31, v46
	v_ashrrev_i32_e32 v45, 31, v44
	v_ashrrev_i32_e32 v51, 31, v50
	v_ashrrev_i32_e32 v49, 31, v48
	v_ashrrev_i32_e32 v55, 31, v54
	v_ashrrev_i32_e32 v53, 31, v52
	v_ashrrev_i32_e32 v59, 31, v58
	v_ashrrev_i32_e32 v57, 31, v56
	v_ashrrev_i32_e32 v63, 31, v62
	v_ashrrev_i32_e32 v61, 31, v60
	v_ashrrev_i32_e32 v67, 31, v66
	v_ashrrev_i32_e32 v65, 31, v64
	v_lshlrev_b64 v[36:37], 15, v[36:37]
	v_lshl_add_u64 v[38:39], v[30:31], 0, v[38:39]
	v_lshlrev_b64 v[40:41], 15, v[40:41]
	v_lshlrev_b64 v[42:43], 15, v[42:43]
	v_lshlrev_b64 v[44:45], 15, v[44:45]
	v_lshlrev_b64 v[46:47], 15, v[46:47]
	v_lshlrev_b64 v[48:49], 15, v[48:49]
	v_lshlrev_b64 v[50:51], 15, v[50:51]
	v_lshlrev_b64 v[52:53], 15, v[52:53]
	v_lshlrev_b64 v[54:55], 15, v[54:55]
	v_lshlrev_b64 v[56:57], 15, v[56:57]
	v_lshlrev_b64 v[58:59], 15, v[58:59]
	v_lshlrev_b64 v[60:61], 15, v[60:61]
	v_lshlrev_b64 v[62:63], 15, v[62:63]
	v_lshlrev_b64 v[64:65], 15, v[64:65]
	v_lshlrev_b64 v[66:67], 15, v[66:67]
	v_lshl_add_u64 v[36:37], v[30:31], 0, v[36:37]
	v_lshl_add_u64 v[42:43], v[30:31], 0, v[42:43]
	v_lshl_add_u64 v[40:41], v[30:31], 0, v[40:41]
	v_lshl_add_u64 v[46:47], v[30:31], 0, v[46:47]
	v_lshl_add_u64 v[44:45], v[30:31], 0, v[44:45]
	v_lshl_add_u64 v[50:51], v[30:31], 0, v[50:51]
	v_lshl_add_u64 v[48:49], v[30:31], 0, v[48:49]
	v_lshl_add_u64 v[54:55], v[30:31], 0, v[54:55]
	v_lshl_add_u64 v[52:53], v[30:31], 0, v[52:53]
	v_lshl_add_u64 v[58:59], v[30:31], 0, v[58:59]
	v_lshl_add_u64 v[56:57], v[30:31], 0, v[56:57]
	v_lshl_add_u64 v[62:63], v[30:31], 0, v[62:63]
	v_lshl_add_u64 v[60:61], v[30:31], 0, v[60:61]
	v_lshl_add_u64 v[66:67], v[30:31], 0, v[66:67]
	v_lshl_add_u64 v[64:65], v[30:31], 0, v[64:65]
	global_load_dword v81, v[38:39], off
	global_load_dword v82, v[36:37], off
	global_load_dword v83, v[42:43], off
	global_load_dword v84, v[40:41], off
	global_load_dword v85, v[46:47], off
	global_load_dword v86, v[44:45], off
	global_load_dword v87, v[50:51], off
	global_load_dword v88, v[48:49], off
	global_load_dword v89, v[54:55], off
	global_load_dword v90, v[52:53], off
	global_load_dword v91, v[58:59], off
	global_load_dword v92, v[56:57], off
	global_load_dword v93, v[62:63], off
	global_load_dword v94, v[60:61], off
	global_load_dword v95, v[66:67], off
	global_load_dword v96, v[64:65], off
	s_add_i32 s11, s11, 16
	s_add_i32 s7, s7, 16
	s_lshl_b32 s15, s7, 1
	s_lshl_b32 s16, s11, 1
	v_or_b32_e32 v160, s15, v1
	v_or_b32_e32 v161, s16, v0
	s_add_i32 s17, s15, 4
	s_add_i32 s18, s16, 4
	s_add_i32 s19, s15, 8
	s_add_i32 s20, s16, 8
	s_add_i32 s21, s15, 12
	s_add_i32 s22, s16, 12
	s_add_i32 s23, s15, 16
	s_add_i32 s24, s16, 16
	s_add_i32 s25, s15, 20
	s_add_i32 s26, s16, 20
	s_add_i32 s27, s15, 24
	s_add_i32 s28, s16, 24
	s_add_i32 s15, s15, 28
	s_add_i32 s16, s16, 28
	v_add_u32_e32 v100, s6, v161
	v_or_b32_e32 v162, s17, v1
	v_or_b32_e32 v130, s18, v0
	v_or_b32_e32 v131, s19, v1
	v_or_b32_e32 v132, s20, v0
	v_or_b32_e32 v133, s21, v1
	v_or_b32_e32 v134, s22, v0
	v_or_b32_e32 v135, s23, v1
	v_or_b32_e32 v136, s24, v0
	v_or_b32_e32 v137, s25, v1
	v_or_b32_e32 v138, s26, v0
	v_or_b32_e32 v139, s27, v1
	v_or_b32_e32 v140, s28, v0
	v_or_b32_e32 v141, s15, v1
	v_or_b32_e32 v142, s16, v0
	v_add_u32_e32 v98, s3, v160
	v_ashrrev_i32_e32 v101, 31, v100
	v_add_u32_e32 v102, s3, v162
	v_add_u32_e32 v104, s6, v130
	v_add_u32_e32 v106, s3, v131
	v_add_u32_e32 v108, s6, v132
	v_add_u32_e32 v110, s3, v133
	v_add_u32_e32 v112, s6, v134
	v_add_u32_e32 v114, s3, v135
	v_add_u32_e32 v116, s6, v136
	v_add_u32_e32 v118, s3, v137
	v_add_u32_e32 v120, s6, v138
	v_add_u32_e32 v122, s3, v139
	v_add_u32_e32 v124, s6, v140
	v_add_u32_e32 v126, s3, v141
	v_add_u32_e32 v128, s6, v142
	v_ashrrev_i32_e32 v99, 31, v98
	v_lshlrev_b64 v[100:101], 15, v[100:101]
	v_ashrrev_i32_e32 v105, 31, v104
	v_ashrrev_i32_e32 v103, 31, v102
	v_ashrrev_i32_e32 v109, 31, v108
	v_ashrrev_i32_e32 v107, 31, v106
	v_ashrrev_i32_e32 v113, 31, v112
	v_ashrrev_i32_e32 v111, 31, v110
	v_ashrrev_i32_e32 v117, 31, v116
	v_ashrrev_i32_e32 v115, 31, v114
	v_ashrrev_i32_e32 v121, 31, v120
	v_ashrrev_i32_e32 v119, 31, v118
	v_ashrrev_i32_e32 v125, 31, v124
	v_ashrrev_i32_e32 v123, 31, v122
	v_ashrrev_i32_e32 v129, 31, v128
	v_ashrrev_i32_e32 v127, 31, v126
	v_lshlrev_b64 v[98:99], 15, v[98:99]
	v_lshl_add_u64 v[100:101], v[30:31], 0, v[100:101]
	v_lshlrev_b64 v[102:103], 15, v[102:103]
	v_lshlrev_b64 v[104:105], 15, v[104:105]
	v_lshlrev_b64 v[106:107], 15, v[106:107]
	v_lshlrev_b64 v[108:109], 15, v[108:109]
	v_lshlrev_b64 v[110:111], 15, v[110:111]
	v_lshlrev_b64 v[112:113], 15, v[112:113]
	v_lshlrev_b64 v[114:115], 15, v[114:115]
	v_lshlrev_b64 v[116:117], 15, v[116:117]
	v_lshlrev_b64 v[118:119], 15, v[118:119]
	v_lshlrev_b64 v[120:121], 15, v[120:121]
	v_lshlrev_b64 v[122:123], 15, v[122:123]
	v_lshlrev_b64 v[124:125], 15, v[124:125]
	v_lshlrev_b64 v[126:127], 15, v[126:127]
	v_lshlrev_b64 v[128:129], 15, v[128:129]
	v_lshl_add_u64 v[98:99], v[30:31], 0, v[98:99]
	v_lshl_add_u64 v[104:105], v[30:31], 0, v[104:105]
	v_lshl_add_u64 v[102:103], v[30:31], 0, v[102:103]
	v_lshl_add_u64 v[108:109], v[30:31], 0, v[108:109]
	v_lshl_add_u64 v[106:107], v[30:31], 0, v[106:107]
	v_lshl_add_u64 v[112:113], v[30:31], 0, v[112:113]
	v_lshl_add_u64 v[110:111], v[30:31], 0, v[110:111]
	v_lshl_add_u64 v[116:117], v[30:31], 0, v[116:117]
	v_lshl_add_u64 v[114:115], v[30:31], 0, v[114:115]
	v_lshl_add_u64 v[120:121], v[30:31], 0, v[120:121]
	v_lshl_add_u64 v[118:119], v[30:31], 0, v[118:119]
	v_lshl_add_u64 v[124:125], v[30:31], 0, v[124:125]
	v_lshl_add_u64 v[122:123], v[30:31], 0, v[122:123]
	v_lshl_add_u64 v[128:129], v[30:31], 0, v[128:129]
	v_lshl_add_u64 v[126:127], v[30:31], 0, v[126:127]
	global_load_dword v143, v[100:101], off
	global_load_dword v144, v[98:99], off
	global_load_dword v145, v[104:105], off
	global_load_dword v146, v[102:103], off
	global_load_dword v147, v[108:109], off
	global_load_dword v148, v[106:107], off
	global_load_dword v149, v[112:113], off
	global_load_dword v150, v[110:111], off
	global_load_dword v151, v[116:117], off
	global_load_dword v152, v[114:115], off
	global_load_dword v153, v[120:121], off
	global_load_dword v154, v[118:119], off
	global_load_dword v155, v[124:125], off
	global_load_dword v156, v[122:123], off
	global_load_dword v157, v[128:129], off
	global_load_dword v158, v[126:127], off
	v_mad_u64_u32 v[36:37], s[16:17], v27, s10, v[6:7]
	v_mad_u64_u32 v[38:39], s[16:17], v2, s10, v[6:7]
	v_mad_u64_u32 v[40:41], s[16:17], v68, s10, v[6:7]
	v_mad_u64_u32 v[42:43], s[16:17], v29, s10, v[6:7]
	v_mad_u64_u32 v[44:45], s[16:17], v70, s10, v[6:7]
	v_mad_u64_u32 v[46:47], s[16:17], v69, s10, v[6:7]
	v_mad_u64_u32 v[48:49], s[16:17], v72, s10, v[6:7]
	v_mad_u64_u32 v[50:51], s[16:17], v71, s10, v[6:7]
	v_mad_u64_u32 v[52:53], s[16:17], v74, s10, v[6:7]
	v_mad_u64_u32 v[54:55], s[16:17], v73, s10, v[6:7]
	v_mad_u64_u32 v[56:57], s[16:17], v76, s10, v[6:7]
	v_mad_u64_u32 v[58:59], s[16:17], v75, s10, v[6:7]
	v_mad_u64_u32 v[60:61], s[16:17], v78, s10, v[6:7]
	v_mad_u64_u32 v[62:63], s[16:17], v77, s10, v[6:7]
	v_mad_u64_u32 v[64:65], s[16:17], v80, s10, v[6:7]
	v_mad_u64_u32 v[66:67], s[16:17], v79, s10, v[6:7]
	s_waitcnt vmcnt(31)
	ds_write_b32 v36, v81
	s_waitcnt vmcnt(30)
	ds_write_b32 v38, v82
	s_waitcnt vmcnt(29)
	ds_write_b32 v40, v83
	s_waitcnt vmcnt(28)
	ds_write_b32 v42, v84
	s_waitcnt vmcnt(27)
	ds_write_b32 v44, v85
	s_waitcnt vmcnt(26)
	ds_write_b32 v46, v86
	s_waitcnt vmcnt(25)
	ds_write_b32 v48, v87
	s_waitcnt vmcnt(24)
	ds_write_b32 v50, v88
	s_waitcnt vmcnt(23)
	ds_write_b32 v52, v89
	s_waitcnt vmcnt(22)
	ds_write_b32 v54, v90
	s_waitcnt vmcnt(21)
	ds_write_b32 v56, v91
	s_waitcnt vmcnt(20)
	ds_write_b32 v58, v92
	s_waitcnt vmcnt(19)
	ds_write_b32 v60, v93
	s_waitcnt vmcnt(18)
	ds_write_b32 v62, v94
	s_waitcnt vmcnt(17)
	ds_write_b32 v64, v95
	s_waitcnt vmcnt(16)
	ds_write_b32 v66, v96
	v_mad_u64_u32 v[98:99], s[16:17], v161, s10, v[6:7]
	v_mad_u64_u32 v[100:101], s[16:17], v160, s10, v[6:7]
	v_mad_u64_u32 v[102:103], s[16:17], v130, s10, v[6:7]
	v_mad_u64_u32 v[104:105], s[16:17], v162, s10, v[6:7]
	v_mad_u64_u32 v[106:107], s[16:17], v132, s10, v[6:7]
	v_mad_u64_u32 v[108:109], s[16:17], v131, s10, v[6:7]
	v_mad_u64_u32 v[110:111], s[16:17], v134, s10, v[6:7]
	v_mad_u64_u32 v[112:113], s[16:17], v133, s10, v[6:7]
	v_mad_u64_u32 v[114:115], s[16:17], v136, s10, v[6:7]
	v_mad_u64_u32 v[116:117], s[16:17], v135, s10, v[6:7]
	v_mad_u64_u32 v[118:119], s[16:17], v138, s10, v[6:7]
	v_mad_u64_u32 v[120:121], s[16:17], v137, s10, v[6:7]
	v_mad_u64_u32 v[122:123], s[16:17], v140, s10, v[6:7]
	v_mad_u64_u32 v[124:125], s[16:17], v139, s10, v[6:7]
	v_mad_u64_u32 v[126:127], s[16:17], v142, s10, v[6:7]
	v_mad_u64_u32 v[128:129], s[16:17], v141, s10, v[6:7]
	s_waitcnt vmcnt(15)
	ds_write_b32 v98, v143
	s_waitcnt vmcnt(14)
	ds_write_b32 v100, v144
	s_waitcnt vmcnt(13)
	ds_write_b32 v102, v145
	s_waitcnt vmcnt(12)
	ds_write_b32 v104, v146
	s_waitcnt vmcnt(11)
	ds_write_b32 v106, v147
	s_waitcnt vmcnt(10)
	ds_write_b32 v108, v148
	s_waitcnt vmcnt(9)
	ds_write_b32 v110, v149
	s_waitcnt vmcnt(8)
	ds_write_b32 v112, v150
	s_waitcnt vmcnt(7)
	ds_write_b32 v114, v151
	s_waitcnt vmcnt(6)
	ds_write_b32 v116, v152
	s_waitcnt vmcnt(5)
	ds_write_b32 v118, v153
	s_waitcnt vmcnt(4)
	ds_write_b32 v120, v154
	s_waitcnt vmcnt(3)
	ds_write_b32 v122, v155
	s_waitcnt vmcnt(2)
	ds_write_b32 v124, v156
	s_waitcnt vmcnt(1)
	ds_write_b32 v126, v157
	s_waitcnt vmcnt(0)
	ds_write_b32 v128, v158
	s_add_i32 s11, s11, 16
	s_add_i32 s7, s7, 16
	s_add_i32 s14, s14, -16
	s_add_i32 s14, s14, -16
	s_cmp_lg_u32 s14, 0
	s_waitcnt lgkmcnt(0)
	ds_read2_b32 v[30:31], v32 offset1:33
	s_waitcnt lgkmcnt(0)
	v_cvt_pk_bf16_f32 v36, v30, v31
	ds_read2_b32 v[30:31], v32 offset0:66 offset1:99
	v_or_b32_e32 v40, s2, v7
	s_waitcnt lgkmcnt(0)
	v_cvt_pk_bf16_f32 v37, v30, v31
	ds_read2_b32 v[30:31], v32 offset0:132 offset1:165
	s_ashr_i32 s7, s6, 31
	v_ashrrev_i32_e32 v41, 31, v40
	s_waitcnt lgkmcnt(0)
	v_cvt_pk_bf16_f32 v38, v30, v31
	ds_read2_b32 v[30:31], v32 offset0:198 offset1:231
	v_lshl_add_u64 v[42:43], s[6:7], 1, v[8:9]
	v_lshlrev_b64 v[40:41], 12, v[40:41]
	s_waitcnt lgkmcnt(0)
	v_cvt_pk_bf16_f32 v39, v30, v31
	ds_read2_b32 v[30:31], v32 offset0:8 offset1:41
	v_lshl_add_u64 v[40:41], v[42:43], 0, v[40:41]
	global_store_dwordx4 v[40:41], v[36:39], off
	v_or_b32_e32 v40, s2, v33
	v_ashrrev_i32_e32 v41, 31, v40
	s_waitcnt lgkmcnt(0)
	v_cvt_pk_bf16_f32 v36, v30, v31
	ds_read2_b32 v[30:31], v32 offset0:74 offset1:107
	s_waitcnt lgkmcnt(0)
	v_cvt_pk_bf16_f32 v37, v30, v31
	ds_read2_b32 v[30:31], v32 offset0:140 offset1:173
	s_waitcnt lgkmcnt(0)
	v_cvt_pk_bf16_f32 v38, v30, v31
	ds_read2_b32 v[30:31], v32 offset0:206 offset1:239
	v_lshlrev_b64 v[40:41], 12, v[40:41]
	s_waitcnt lgkmcnt(0)
	v_cvt_pk_bf16_f32 v39, v30, v31
	ds_read2_b32 v[30:31], v32 offset0:16 offset1:49
	v_lshl_add_u64 v[40:41], v[42:43], 0, v[40:41]
	global_store_dwordx4 v[40:41], v[36:39], off
	v_or_b32_e32 v40, s2, v34
	v_ashrrev_i32_e32 v41, 31, v40
	s_waitcnt lgkmcnt(0)
	v_cvt_pk_bf16_f32 v36, v30, v31
	ds_read2_b32 v[30:31], v32 offset0:82 offset1:115
	s_waitcnt lgkmcnt(0)
	v_cvt_pk_bf16_f32 v37, v30, v31
	ds_read2_b32 v[30:31], v32 offset0:148 offset1:181
	s_waitcnt lgkmcnt(0)
	v_cvt_pk_bf16_f32 v38, v30, v31
	ds_read2_b32 v[30:31], v32 offset0:214 offset1:247
	v_lshlrev_b64 v[40:41], 12, v[40:41]
	s_waitcnt lgkmcnt(0)
	v_cvt_pk_bf16_f32 v39, v30, v31
	ds_read2_b32 v[30:31], v32 offset0:24 offset1:57
	v_lshl_add_u64 v[40:41], v[42:43], 0, v[40:41]
	global_store_dwordx4 v[40:41], v[36:39], off
	v_or_b32_e32 v40, s2, v35
	v_ashrrev_i32_e32 v41, 31, v40
	s_waitcnt lgkmcnt(0)
	v_cvt_pk_bf16_f32 v36, v30, v31
	ds_read2_b32 v[30:31], v32 offset0:90 offset1:123
	s_waitcnt lgkmcnt(0)
	v_cvt_pk_bf16_f32 v37, v30, v31
	ds_read2_b32 v[30:31], v32 offset0:156 offset1:189
	s_waitcnt lgkmcnt(0)
	v_cvt_pk_bf16_f32 v38, v30, v31
	ds_read2_b32 v[30:31], v32 offset0:222 offset1:255
	v_lshlrev_b64 v[40:41], 12, v[40:41]
	s_waitcnt lgkmcnt(0)
	v_cvt_pk_bf16_f32 v39, v30, v31
	v_lshl_add_u64 v[30:31], v[42:43], 0, v[40:41]
	global_store_dwordx4 v[30:31], v[36:39], off
	s_waitcnt lgkmcnt(0)
	s_mov_b32 s11, s8
	s_andn2_b64 vcc, exec, s[0:1]
	s_cbranch_vccnz .LBB0_335

.LBB0_348:
	s_lshl_b32 s16, s7, 1
	s_lshl_b32 s17, s14, 1
	v_or_b32_e32 v2, s16, v1
	v_or_b32_e32 v27, s17, v0
	s_add_i32 s18, s16, 4
	s_add_i32 s19, s17, 4
	s_add_i32 s20, s16, 8
	s_add_i32 s21, s17, 8
	s_add_i32 s22, s16, 12
	s_add_i32 s23, s17, 12
	s_add_i32 s24, s16, 16
	s_add_i32 s25, s17, 16
	s_add_i32 s26, s16, 20
	s_add_i32 s27, s17, 20
	s_add_i32 s28, s16, 24
	s_add_i32 s29, s17, 24
	s_add_i32 s16, s16, 28
	s_add_i32 s17, s17, 28
	v_add_u32_e32 v38, s6, v27
	v_or_b32_e32 v29, s18, v1
	v_or_b32_e32 v68, s19, v0
	v_or_b32_e32 v69, s20, v1
	v_or_b32_e32 v70, s21, v0
	v_or_b32_e32 v71, s22, v1
	v_or_b32_e32 v72, s23, v0
	v_or_b32_e32 v73, s24, v1
	v_or_b32_e32 v74, s25, v0
	v_or_b32_e32 v75, s26, v1
	v_or_b32_e32 v76, s27, v0
	v_or_b32_e32 v77, s28, v1
	v_or_b32_e32 v78, s29, v0
	v_or_b32_e32 v79, s16, v1
	v_or_b32_e32 v80, s17, v0
	v_add_u32_e32 v36, s3, v2
	v_ashrrev_i32_e32 v39, 31, v38
	v_add_u32_e32 v40, s3, v29
	v_add_u32_e32 v42, s6, v68
	v_add_u32_e32 v44, s3, v69
	v_add_u32_e32 v46, s6, v70
	v_add_u32_e32 v48, s3, v71
	v_add_u32_e32 v50, s6, v72
	v_add_u32_e32 v52, s3, v73
	v_add_u32_e32 v54, s6, v74
	v_add_u32_e32 v56, s3, v75
	v_add_u32_e32 v58, s6, v76
	v_add_u32_e32 v60, s3, v77
	v_add_u32_e32 v62, s6, v78
	v_add_u32_e32 v64, s3, v79
	v_add_u32_e32 v66, s6, v80
	v_ashrrev_i32_e32 v37, 31, v36
	v_lshlrev_b64 v[38:39], 12, v[38:39]
	v_ashrrev_i32_e32 v43, 31, v42
	v_ashrrev_i32_e32 v41, 31, v40
	v_ashrrev_i32_e32 v47, 31, v46
	v_ashrrev_i32_e32 v45, 31, v44
	v_ashrrev_i32_e32 v51, 31, v50
	v_ashrrev_i32_e32 v49, 31, v48
	v_ashrrev_i32_e32 v55, 31, v54
	v_ashrrev_i32_e32 v53, 31, v52
	v_ashrrev_i32_e32 v59, 31, v58
	v_ashrrev_i32_e32 v57, 31, v56
	v_ashrrev_i32_e32 v63, 31, v62
	v_ashrrev_i32_e32 v61, 31, v60
	v_ashrrev_i32_e32 v67, 31, v66
	v_ashrrev_i32_e32 v65, 31, v64
	v_lshlrev_b64 v[36:37], 12, v[36:37]
	v_lshl_add_u64 v[38:39], v[30:31], 0, v[38:39]
	v_lshlrev_b64 v[40:41], 12, v[40:41]
	v_lshlrev_b64 v[42:43], 12, v[42:43]
	v_lshlrev_b64 v[44:45], 12, v[44:45]
	v_lshlrev_b64 v[46:47], 12, v[46:47]
	v_lshlrev_b64 v[48:49], 12, v[48:49]
	v_lshlrev_b64 v[50:51], 12, v[50:51]
	v_lshlrev_b64 v[52:53], 12, v[52:53]
	v_lshlrev_b64 v[54:55], 12, v[54:55]
	v_lshlrev_b64 v[56:57], 12, v[56:57]
	v_lshlrev_b64 v[58:59], 12, v[58:59]
	v_lshlrev_b64 v[60:61], 12, v[60:61]
	v_lshlrev_b64 v[62:63], 12, v[62:63]
	v_lshlrev_b64 v[64:65], 12, v[64:65]
	v_lshlrev_b64 v[66:67], 12, v[66:67]
	v_lshl_add_u64 v[36:37], v[30:31], 0, v[36:37]
	v_lshl_add_u64 v[42:43], v[30:31], 0, v[42:43]
	v_lshl_add_u64 v[40:41], v[30:31], 0, v[40:41]
	v_lshl_add_u64 v[46:47], v[30:31], 0, v[46:47]
	v_lshl_add_u64 v[44:45], v[30:31], 0, v[44:45]
	v_lshl_add_u64 v[50:51], v[30:31], 0, v[50:51]
	v_lshl_add_u64 v[48:49], v[30:31], 0, v[48:49]
	v_lshl_add_u64 v[54:55], v[30:31], 0, v[54:55]
	v_lshl_add_u64 v[52:53], v[30:31], 0, v[52:53]
	v_lshl_add_u64 v[58:59], v[30:31], 0, v[58:59]
	v_lshl_add_u64 v[56:57], v[30:31], 0, v[56:57]
	v_lshl_add_u64 v[62:63], v[30:31], 0, v[62:63]
	v_lshl_add_u64 v[60:61], v[30:31], 0, v[60:61]
	v_lshl_add_u64 v[66:67], v[30:31], 0, v[66:67]
	v_lshl_add_u64 v[64:65], v[30:31], 0, v[64:65]
	global_load_dword v81, v[38:39], off
	global_load_dword v82, v[36:37], off
	global_load_dword v83, v[42:43], off
	global_load_dword v84, v[40:41], off
	global_load_dword v85, v[46:47], off
	global_load_dword v86, v[44:45], off
	global_load_dword v87, v[50:51], off
	global_load_dword v88, v[48:49], off
	global_load_dword v89, v[54:55], off
	global_load_dword v90, v[52:53], off
	global_load_dword v91, v[58:59], off
	global_load_dword v92, v[56:57], off
	global_load_dword v93, v[62:63], off
	global_load_dword v94, v[60:61], off
	global_load_dword v95, v[66:67], off
	global_load_dword v96, v[64:65], off
	s_add_i32 s14, s14, 16
	s_add_i32 s7, s7, 16
	s_lshl_b32 s16, s7, 1
	s_lshl_b32 s17, s14, 1
	v_or_b32_e32 v160, s16, v1
	v_or_b32_e32 v161, s17, v0
	s_add_i32 s18, s16, 4
	s_add_i32 s19, s17, 4
	s_add_i32 s20, s16, 8
	s_add_i32 s21, s17, 8
	s_add_i32 s22, s16, 12
	s_add_i32 s23, s17, 12
	s_add_i32 s24, s16, 16
	s_add_i32 s25, s17, 16
	s_add_i32 s26, s16, 20
	s_add_i32 s27, s17, 20
	s_add_i32 s28, s16, 24
	s_add_i32 s29, s17, 24
	s_add_i32 s16, s16, 28
	s_add_i32 s17, s17, 28
	v_add_u32_e32 v100, s6, v161
	v_or_b32_e32 v162, s18, v1
	v_or_b32_e32 v130, s19, v0
	v_or_b32_e32 v131, s20, v1
	v_or_b32_e32 v132, s21, v0
	v_or_b32_e32 v133, s22, v1
	v_or_b32_e32 v134, s23, v0
	v_or_b32_e32 v135, s24, v1
	v_or_b32_e32 v136, s25, v0
	v_or_b32_e32 v137, s26, v1
	v_or_b32_e32 v138, s27, v0
	v_or_b32_e32 v139, s28, v1
	v_or_b32_e32 v140, s29, v0
	v_or_b32_e32 v141, s16, v1
	v_or_b32_e32 v142, s17, v0
	v_add_u32_e32 v98, s3, v160
	v_ashrrev_i32_e32 v101, 31, v100
	v_add_u32_e32 v102, s3, v162
	v_add_u32_e32 v104, s6, v130
	v_add_u32_e32 v106, s3, v131
	v_add_u32_e32 v108, s6, v132
	v_add_u32_e32 v110, s3, v133
	v_add_u32_e32 v112, s6, v134
	v_add_u32_e32 v114, s3, v135
	v_add_u32_e32 v116, s6, v136
	v_add_u32_e32 v118, s3, v137
	v_add_u32_e32 v120, s6, v138
	v_add_u32_e32 v122, s3, v139
	v_add_u32_e32 v124, s6, v140
	v_add_u32_e32 v126, s3, v141
	v_add_u32_e32 v128, s6, v142
	v_ashrrev_i32_e32 v99, 31, v98
	v_lshlrev_b64 v[100:101], 12, v[100:101]
	v_ashrrev_i32_e32 v105, 31, v104
	v_ashrrev_i32_e32 v103, 31, v102
	v_ashrrev_i32_e32 v109, 31, v108
	v_ashrrev_i32_e32 v107, 31, v106
	v_ashrrev_i32_e32 v113, 31, v112
	v_ashrrev_i32_e32 v111, 31, v110
	v_ashrrev_i32_e32 v117, 31, v116
	v_ashrrev_i32_e32 v115, 31, v114
	v_ashrrev_i32_e32 v121, 31, v120
	v_ashrrev_i32_e32 v119, 31, v118
	v_ashrrev_i32_e32 v125, 31, v124
	v_ashrrev_i32_e32 v123, 31, v122
	v_ashrrev_i32_e32 v129, 31, v128
	v_ashrrev_i32_e32 v127, 31, v126
	v_lshlrev_b64 v[98:99], 12, v[98:99]
	v_lshl_add_u64 v[100:101], v[30:31], 0, v[100:101]
	v_lshlrev_b64 v[102:103], 12, v[102:103]
	v_lshlrev_b64 v[104:105], 12, v[104:105]
	v_lshlrev_b64 v[106:107], 12, v[106:107]
	v_lshlrev_b64 v[108:109], 12, v[108:109]
	v_lshlrev_b64 v[110:111], 12, v[110:111]
	v_lshlrev_b64 v[112:113], 12, v[112:113]
	v_lshlrev_b64 v[114:115], 12, v[114:115]
	v_lshlrev_b64 v[116:117], 12, v[116:117]
	v_lshlrev_b64 v[118:119], 12, v[118:119]
	v_lshlrev_b64 v[120:121], 12, v[120:121]
	v_lshlrev_b64 v[122:123], 12, v[122:123]
	v_lshlrev_b64 v[124:125], 12, v[124:125]
	v_lshlrev_b64 v[126:127], 12, v[126:127]
	v_lshlrev_b64 v[128:129], 12, v[128:129]
	v_lshl_add_u64 v[98:99], v[30:31], 0, v[98:99]
	v_lshl_add_u64 v[104:105], v[30:31], 0, v[104:105]
	v_lshl_add_u64 v[102:103], v[30:31], 0, v[102:103]
	v_lshl_add_u64 v[108:109], v[30:31], 0, v[108:109]
	v_lshl_add_u64 v[106:107], v[30:31], 0, v[106:107]
	v_lshl_add_u64 v[112:113], v[30:31], 0, v[112:113]
	v_lshl_add_u64 v[110:111], v[30:31], 0, v[110:111]
	v_lshl_add_u64 v[116:117], v[30:31], 0, v[116:117]
	v_lshl_add_u64 v[114:115], v[30:31], 0, v[114:115]
	v_lshl_add_u64 v[120:121], v[30:31], 0, v[120:121]
	v_lshl_add_u64 v[118:119], v[30:31], 0, v[118:119]
	v_lshl_add_u64 v[124:125], v[30:31], 0, v[124:125]
	v_lshl_add_u64 v[122:123], v[30:31], 0, v[122:123]
	v_lshl_add_u64 v[128:129], v[30:31], 0, v[128:129]
	v_lshl_add_u64 v[126:127], v[30:31], 0, v[126:127]
	global_load_dword v143, v[100:101], off
	global_load_dword v144, v[98:99], off
	global_load_dword v145, v[104:105], off
	global_load_dword v146, v[102:103], off
	global_load_dword v147, v[108:109], off
	global_load_dword v148, v[106:107], off
	global_load_dword v149, v[112:113], off
	global_load_dword v150, v[110:111], off
	global_load_dword v151, v[116:117], off
	global_load_dword v152, v[114:115], off
	global_load_dword v153, v[120:121], off
	global_load_dword v154, v[118:119], off
	global_load_dword v155, v[124:125], off
	global_load_dword v156, v[122:123], off
	global_load_dword v157, v[128:129], off
	global_load_dword v158, v[126:127], off
	v_mad_u64_u32 v[36:37], s[16:17], v27, s10, v[6:7]
	v_mad_u64_u32 v[38:39], s[16:17], v2, s10, v[6:7]
	v_mad_u64_u32 v[40:41], s[16:17], v68, s10, v[6:7]
	v_mad_u64_u32 v[42:43], s[16:17], v29, s10, v[6:7]
	v_mad_u64_u32 v[44:45], s[16:17], v70, s10, v[6:7]
	v_mad_u64_u32 v[46:47], s[16:17], v69, s10, v[6:7]
	v_mad_u64_u32 v[48:49], s[16:17], v72, s10, v[6:7]
	v_mad_u64_u32 v[50:51], s[16:17], v71, s10, v[6:7]
	v_mad_u64_u32 v[52:53], s[16:17], v74, s10, v[6:7]
	v_mad_u64_u32 v[54:55], s[16:17], v73, s10, v[6:7]
	v_mad_u64_u32 v[56:57], s[16:17], v76, s10, v[6:7]
	v_mad_u64_u32 v[58:59], s[16:17], v75, s10, v[6:7]
	v_mad_u64_u32 v[60:61], s[16:17], v78, s10, v[6:7]
	v_mad_u64_u32 v[62:63], s[16:17], v77, s10, v[6:7]
	v_mad_u64_u32 v[64:65], s[16:17], v80, s10, v[6:7]
	v_mad_u64_u32 v[66:67], s[16:17], v79, s10, v[6:7]
	s_waitcnt vmcnt(31)
	ds_write_b32 v36, v81
	s_waitcnt vmcnt(30)
	ds_write_b32 v38, v82
	s_waitcnt vmcnt(29)
	ds_write_b32 v40, v83
	s_waitcnt vmcnt(28)
	ds_write_b32 v42, v84
	s_waitcnt vmcnt(27)
	ds_write_b32 v44, v85
	s_waitcnt vmcnt(26)
	ds_write_b32 v46, v86
	s_waitcnt vmcnt(25)
	ds_write_b32 v48, v87
	s_waitcnt vmcnt(24)
	ds_write_b32 v50, v88
	s_waitcnt vmcnt(23)
	ds_write_b32 v52, v89
	s_waitcnt vmcnt(22)
	ds_write_b32 v54, v90
	s_waitcnt vmcnt(21)
	ds_write_b32 v56, v91
	s_waitcnt vmcnt(20)
	ds_write_b32 v58, v92
	s_waitcnt vmcnt(19)
	ds_write_b32 v60, v93
	s_waitcnt vmcnt(18)
	ds_write_b32 v62, v94
	s_waitcnt vmcnt(17)
	ds_write_b32 v64, v95
	s_waitcnt vmcnt(16)
	ds_write_b32 v66, v96
	v_mad_u64_u32 v[98:99], s[16:17], v161, s10, v[6:7]
	v_mad_u64_u32 v[100:101], s[16:17], v160, s10, v[6:7]
	v_mad_u64_u32 v[102:103], s[16:17], v130, s10, v[6:7]
	v_mad_u64_u32 v[104:105], s[16:17], v162, s10, v[6:7]
	v_mad_u64_u32 v[106:107], s[16:17], v132, s10, v[6:7]
	v_mad_u64_u32 v[108:109], s[16:17], v131, s10, v[6:7]
	v_mad_u64_u32 v[110:111], s[16:17], v134, s10, v[6:7]
	v_mad_u64_u32 v[112:113], s[16:17], v133, s10, v[6:7]
	v_mad_u64_u32 v[114:115], s[16:17], v136, s10, v[6:7]
	v_mad_u64_u32 v[116:117], s[16:17], v135, s10, v[6:7]
	v_mad_u64_u32 v[118:119], s[16:17], v138, s10, v[6:7]
	v_mad_u64_u32 v[120:121], s[16:17], v137, s10, v[6:7]
	v_mad_u64_u32 v[122:123], s[16:17], v140, s10, v[6:7]
	v_mad_u64_u32 v[124:125], s[16:17], v139, s10, v[6:7]
	v_mad_u64_u32 v[126:127], s[16:17], v142, s10, v[6:7]
	v_mad_u64_u32 v[128:129], s[16:17], v141, s10, v[6:7]
	s_waitcnt vmcnt(15)
	ds_write_b32 v98, v143
	s_waitcnt vmcnt(14)
	ds_write_b32 v100, v144
	s_waitcnt vmcnt(13)
	ds_write_b32 v102, v145
	s_waitcnt vmcnt(12)
	ds_write_b32 v104, v146
	s_waitcnt vmcnt(11)
	ds_write_b32 v106, v147
	s_waitcnt vmcnt(10)
	ds_write_b32 v108, v148
	s_waitcnt vmcnt(9)
	ds_write_b32 v110, v149
	s_waitcnt vmcnt(8)
	ds_write_b32 v112, v150
	s_waitcnt vmcnt(7)
	ds_write_b32 v114, v151
	s_waitcnt vmcnt(6)
	ds_write_b32 v116, v152
	s_waitcnt vmcnt(5)
	ds_write_b32 v118, v153
	s_waitcnt vmcnt(4)
	ds_write_b32 v120, v154
	s_waitcnt vmcnt(3)
	ds_write_b32 v122, v155
	s_waitcnt vmcnt(2)
	ds_write_b32 v124, v156
	s_waitcnt vmcnt(1)
	ds_write_b32 v126, v157
	s_waitcnt vmcnt(0)
	ds_write_b32 v128, v158
	s_add_i32 s14, s14, 16
	s_add_i32 s7, s7, 16
	s_add_i32 s15, s15, -16
	s_add_i32 s15, s15, -16
	s_cmp_lg_u32 s15, 0
	s_waitcnt lgkmcnt(0)
	ds_read2_b32 v[30:31], v32 offset1:33
	s_waitcnt lgkmcnt(0)
	v_cvt_pk_bf16_f32 v36, v30, v31
	ds_read2_b32 v[30:31], v32 offset0:66 offset1:99
	v_or_b32_e32 v40, s2, v7
	s_waitcnt lgkmcnt(0)
	v_cvt_pk_bf16_f32 v37, v30, v31
	ds_read2_b32 v[30:31], v32 offset0:132 offset1:165
	s_ashr_i32 s7, s6, 31
	v_ashrrev_i32_e32 v41, 31, v40
	s_waitcnt lgkmcnt(0)
	v_cvt_pk_bf16_f32 v38, v30, v31
	ds_read2_b32 v[30:31], v32 offset0:198 offset1:231
	v_lshl_add_u64 v[42:43], s[6:7], 1, v[12:13]
	v_lshlrev_b64 v[40:41], 11, v[40:41]
	s_waitcnt lgkmcnt(0)
	v_cvt_pk_bf16_f32 v39, v30, v31
	ds_read2_b32 v[30:31], v32 offset0:8 offset1:41
	v_lshl_add_u64 v[40:41], v[42:43], 0, v[40:41]
	global_store_dwordx4 v[40:41], v[36:39], off
	v_or_b32_e32 v40, s2, v33
	v_ashrrev_i32_e32 v41, 31, v40
	s_waitcnt lgkmcnt(0)
	v_cvt_pk_bf16_f32 v36, v30, v31
	ds_read2_b32 v[30:31], v32 offset0:74 offset1:107
	s_waitcnt lgkmcnt(0)
	v_cvt_pk_bf16_f32 v37, v30, v31
	ds_read2_b32 v[30:31], v32 offset0:140 offset1:173
	s_waitcnt lgkmcnt(0)
	v_cvt_pk_bf16_f32 v38, v30, v31
	ds_read2_b32 v[30:31], v32 offset0:206 offset1:239
	v_lshlrev_b64 v[40:41], 11, v[40:41]
	s_waitcnt lgkmcnt(0)
	v_cvt_pk_bf16_f32 v39, v30, v31
	ds_read2_b32 v[30:31], v32 offset0:16 offset1:49
	v_lshl_add_u64 v[40:41], v[42:43], 0, v[40:41]
	global_store_dwordx4 v[40:41], v[36:39], off
	v_or_b32_e32 v40, s2, v34
	v_ashrrev_i32_e32 v41, 31, v40
	s_waitcnt lgkmcnt(0)
	v_cvt_pk_bf16_f32 v36, v30, v31
	ds_read2_b32 v[30:31], v32 offset0:82 offset1:115
	s_waitcnt lgkmcnt(0)
	v_cvt_pk_bf16_f32 v37, v30, v31
	ds_read2_b32 v[30:31], v32 offset0:148 offset1:181
	s_waitcnt lgkmcnt(0)
	v_cvt_pk_bf16_f32 v38, v30, v31
	ds_read2_b32 v[30:31], v32 offset0:214 offset1:247
	v_lshlrev_b64 v[40:41], 11, v[40:41]
	s_waitcnt lgkmcnt(0)
	v_cvt_pk_bf16_f32 v39, v30, v31
	ds_read2_b32 v[30:31], v32 offset0:24 offset1:57
	v_lshl_add_u64 v[40:41], v[42:43], 0, v[40:41]
	global_store_dwordx4 v[40:41], v[36:39], off
	v_or_b32_e32 v40, s2, v35
	v_ashrrev_i32_e32 v41, 31, v40
	s_waitcnt lgkmcnt(0)
	v_cvt_pk_bf16_f32 v36, v30, v31
	ds_read2_b32 v[30:31], v32 offset0:90 offset1:123
	s_waitcnt lgkmcnt(0)
	v_cvt_pk_bf16_f32 v37, v30, v31
	ds_read2_b32 v[30:31], v32 offset0:156 offset1:189
	s_waitcnt lgkmcnt(0)
	v_cvt_pk_bf16_f32 v38, v30, v31
	ds_read2_b32 v[30:31], v32 offset0:222 offset1:255
	v_lshlrev_b64 v[40:41], 11, v[40:41]
	s_waitcnt lgkmcnt(0)
	v_cvt_pk_bf16_f32 v39, v30, v31
	v_lshl_add_u64 v[30:31], v[42:43], 0, v[40:41]
	global_store_dwordx4 v[30:31], v[36:39], off
	s_waitcnt lgkmcnt(0)
	s_mov_b32 s14, s11
	s_andn2_b64 vcc, exec, s[0:1]
	s_cbranch_vccnz .LBB0_335

.LBB0_355:
	s_lshl_b32 s16, s7, 1
	s_lshl_b32 s17, s11, 1
	v_or_b32_e32 v2, s16, v1
	v_or_b32_e32 v27, s17, v0
	s_add_i32 s18, s16, 4
	s_add_i32 s19, s17, 4
	s_add_i32 s20, s16, 8
	s_add_i32 s21, s17, 8
	s_add_i32 s22, s16, 12
	s_add_i32 s23, s17, 12
	s_add_i32 s24, s16, 16
	s_add_i32 s25, s17, 16
	s_add_i32 s26, s16, 20
	s_add_i32 s27, s17, 20
	s_add_i32 s28, s16, 24
	s_add_i32 s29, s17, 24
	s_add_i32 s16, s16, 28
	s_add_i32 s17, s17, 28
	v_add_u32_e32 v38, s6, v27
	v_or_b32_e32 v29, s18, v1
	v_or_b32_e32 v68, s19, v0
	v_or_b32_e32 v69, s20, v1
	v_or_b32_e32 v70, s21, v0
	v_or_b32_e32 v71, s22, v1
	v_or_b32_e32 v72, s23, v0
	v_or_b32_e32 v73, s24, v1
	v_or_b32_e32 v74, s25, v0
	v_or_b32_e32 v75, s26, v1
	v_or_b32_e32 v76, s27, v0
	v_or_b32_e32 v77, s28, v1
	v_or_b32_e32 v78, s29, v0
	v_or_b32_e32 v79, s16, v1
	v_or_b32_e32 v80, s17, v0
	v_add_u32_e32 v36, s3, v2
	v_ashrrev_i32_e32 v39, 31, v38
	v_add_u32_e32 v40, s3, v29
	v_add_u32_e32 v42, s6, v68
	v_add_u32_e32 v44, s3, v69
	v_add_u32_e32 v46, s6, v70
	v_add_u32_e32 v48, s3, v71
	v_add_u32_e32 v50, s6, v72
	v_add_u32_e32 v52, s3, v73
	v_add_u32_e32 v54, s6, v74
	v_add_u32_e32 v56, s3, v75
	v_add_u32_e32 v58, s6, v76
	v_add_u32_e32 v60, s3, v77
	v_add_u32_e32 v62, s6, v78
	v_add_u32_e32 v64, s3, v79
	v_add_u32_e32 v66, s6, v80
	v_ashrrev_i32_e32 v37, 31, v36
	v_lshlrev_b64 v[38:39], 13, v[38:39]
	v_ashrrev_i32_e32 v43, 31, v42
	v_ashrrev_i32_e32 v41, 31, v40
	v_ashrrev_i32_e32 v47, 31, v46
	v_ashrrev_i32_e32 v45, 31, v44
	v_ashrrev_i32_e32 v51, 31, v50
	v_ashrrev_i32_e32 v49, 31, v48
	v_ashrrev_i32_e32 v55, 31, v54
	v_ashrrev_i32_e32 v53, 31, v52
	v_ashrrev_i32_e32 v59, 31, v58
	v_ashrrev_i32_e32 v57, 31, v56
	v_ashrrev_i32_e32 v63, 31, v62
	v_ashrrev_i32_e32 v61, 31, v60
	v_ashrrev_i32_e32 v67, 31, v66
	v_ashrrev_i32_e32 v65, 31, v64
	v_lshlrev_b64 v[36:37], 13, v[36:37]
	v_lshl_add_u64 v[38:39], v[30:31], 0, v[38:39]
	v_lshlrev_b64 v[40:41], 13, v[40:41]
	v_lshlrev_b64 v[42:43], 13, v[42:43]
	v_lshlrev_b64 v[44:45], 13, v[44:45]
	v_lshlrev_b64 v[46:47], 13, v[46:47]
	v_lshlrev_b64 v[48:49], 13, v[48:49]
	v_lshlrev_b64 v[50:51], 13, v[50:51]
	v_lshlrev_b64 v[52:53], 13, v[52:53]
	v_lshlrev_b64 v[54:55], 13, v[54:55]
	v_lshlrev_b64 v[56:57], 13, v[56:57]
	v_lshlrev_b64 v[58:59], 13, v[58:59]
	v_lshlrev_b64 v[60:61], 13, v[60:61]
	v_lshlrev_b64 v[62:63], 13, v[62:63]
	v_lshlrev_b64 v[64:65], 13, v[64:65]
	v_lshlrev_b64 v[66:67], 13, v[66:67]
	v_lshl_add_u64 v[36:37], v[30:31], 0, v[36:37]
	v_lshl_add_u64 v[42:43], v[30:31], 0, v[42:43]
	v_lshl_add_u64 v[40:41], v[30:31], 0, v[40:41]
	v_lshl_add_u64 v[46:47], v[30:31], 0, v[46:47]
	v_lshl_add_u64 v[44:45], v[30:31], 0, v[44:45]
	v_lshl_add_u64 v[50:51], v[30:31], 0, v[50:51]
	v_lshl_add_u64 v[48:49], v[30:31], 0, v[48:49]
	v_lshl_add_u64 v[54:55], v[30:31], 0, v[54:55]
	v_lshl_add_u64 v[52:53], v[30:31], 0, v[52:53]
	v_lshl_add_u64 v[58:59], v[30:31], 0, v[58:59]
	v_lshl_add_u64 v[56:57], v[30:31], 0, v[56:57]
	v_lshl_add_u64 v[62:63], v[30:31], 0, v[62:63]
	v_lshl_add_u64 v[60:61], v[30:31], 0, v[60:61]
	v_lshl_add_u64 v[66:67], v[30:31], 0, v[66:67]
	v_lshl_add_u64 v[64:65], v[30:31], 0, v[64:65]
	global_load_dword v81, v[38:39], off
	global_load_dword v82, v[36:37], off
	global_load_dword v83, v[42:43], off
	global_load_dword v84, v[40:41], off
	global_load_dword v85, v[46:47], off
	global_load_dword v86, v[44:45], off
	global_load_dword v87, v[50:51], off
	global_load_dword v88, v[48:49], off
	global_load_dword v89, v[54:55], off
	global_load_dword v90, v[52:53], off
	global_load_dword v91, v[58:59], off
	global_load_dword v92, v[56:57], off
	global_load_dword v93, v[62:63], off
	global_load_dword v94, v[60:61], off
	global_load_dword v95, v[66:67], off
	global_load_dword v96, v[64:65], off
	s_add_i32 s11, s11, 16
	s_add_i32 s7, s7, 16
	s_lshl_b32 s16, s7, 1
	s_lshl_b32 s17, s11, 1
	v_or_b32_e32 v160, s16, v1
	v_or_b32_e32 v161, s17, v0
	s_add_i32 s18, s16, 4
	s_add_i32 s19, s17, 4
	s_add_i32 s20, s16, 8
	s_add_i32 s21, s17, 8
	s_add_i32 s22, s16, 12
	s_add_i32 s23, s17, 12
	s_add_i32 s24, s16, 16
	s_add_i32 s25, s17, 16
	s_add_i32 s26, s16, 20
	s_add_i32 s27, s17, 20
	s_add_i32 s28, s16, 24
	s_add_i32 s29, s17, 24
	s_add_i32 s16, s16, 28
	s_add_i32 s17, s17, 28
	v_add_u32_e32 v100, s6, v161
	v_or_b32_e32 v162, s18, v1
	v_or_b32_e32 v130, s19, v0
	v_or_b32_e32 v131, s20, v1
	v_or_b32_e32 v132, s21, v0
	v_or_b32_e32 v133, s22, v1
	v_or_b32_e32 v134, s23, v0
	v_or_b32_e32 v135, s24, v1
	v_or_b32_e32 v136, s25, v0
	v_or_b32_e32 v137, s26, v1
	v_or_b32_e32 v138, s27, v0
	v_or_b32_e32 v139, s28, v1
	v_or_b32_e32 v140, s29, v0
	v_or_b32_e32 v141, s16, v1
	v_or_b32_e32 v142, s17, v0
	v_add_u32_e32 v98, s3, v160
	v_ashrrev_i32_e32 v101, 31, v100
	v_add_u32_e32 v102, s3, v162
	v_add_u32_e32 v104, s6, v130
	v_add_u32_e32 v106, s3, v131
	v_add_u32_e32 v108, s6, v132
	v_add_u32_e32 v110, s3, v133
	v_add_u32_e32 v112, s6, v134
	v_add_u32_e32 v114, s3, v135
	v_add_u32_e32 v116, s6, v136
	v_add_u32_e32 v118, s3, v137
	v_add_u32_e32 v120, s6, v138
	v_add_u32_e32 v122, s3, v139
	v_add_u32_e32 v124, s6, v140
	v_add_u32_e32 v126, s3, v141
	v_add_u32_e32 v128, s6, v142
	v_ashrrev_i32_e32 v99, 31, v98
	v_lshlrev_b64 v[100:101], 13, v[100:101]
	v_ashrrev_i32_e32 v105, 31, v104
	v_ashrrev_i32_e32 v103, 31, v102
	v_ashrrev_i32_e32 v109, 31, v108
	v_ashrrev_i32_e32 v107, 31, v106
	v_ashrrev_i32_e32 v113, 31, v112
	v_ashrrev_i32_e32 v111, 31, v110
	v_ashrrev_i32_e32 v117, 31, v116
	v_ashrrev_i32_e32 v115, 31, v114
	v_ashrrev_i32_e32 v121, 31, v120
	v_ashrrev_i32_e32 v119, 31, v118
	v_ashrrev_i32_e32 v125, 31, v124
	v_ashrrev_i32_e32 v123, 31, v122
	v_ashrrev_i32_e32 v129, 31, v128
	v_ashrrev_i32_e32 v127, 31, v126
	v_lshlrev_b64 v[98:99], 13, v[98:99]
	v_lshl_add_u64 v[100:101], v[30:31], 0, v[100:101]
	v_lshlrev_b64 v[102:103], 13, v[102:103]
	v_lshlrev_b64 v[104:105], 13, v[104:105]
	v_lshlrev_b64 v[106:107], 13, v[106:107]
	v_lshlrev_b64 v[108:109], 13, v[108:109]
	v_lshlrev_b64 v[110:111], 13, v[110:111]
	v_lshlrev_b64 v[112:113], 13, v[112:113]
	v_lshlrev_b64 v[114:115], 13, v[114:115]
	v_lshlrev_b64 v[116:117], 13, v[116:117]
	v_lshlrev_b64 v[118:119], 13, v[118:119]
	v_lshlrev_b64 v[120:121], 13, v[120:121]
	v_lshlrev_b64 v[122:123], 13, v[122:123]
	v_lshlrev_b64 v[124:125], 13, v[124:125]
	v_lshlrev_b64 v[126:127], 13, v[126:127]
	v_lshlrev_b64 v[128:129], 13, v[128:129]
	v_lshl_add_u64 v[98:99], v[30:31], 0, v[98:99]
	v_lshl_add_u64 v[104:105], v[30:31], 0, v[104:105]
	v_lshl_add_u64 v[102:103], v[30:31], 0, v[102:103]
	v_lshl_add_u64 v[108:109], v[30:31], 0, v[108:109]
	v_lshl_add_u64 v[106:107], v[30:31], 0, v[106:107]
	v_lshl_add_u64 v[112:113], v[30:31], 0, v[112:113]
	v_lshl_add_u64 v[110:111], v[30:31], 0, v[110:111]
	v_lshl_add_u64 v[116:117], v[30:31], 0, v[116:117]
	v_lshl_add_u64 v[114:115], v[30:31], 0, v[114:115]
	v_lshl_add_u64 v[120:121], v[30:31], 0, v[120:121]
	v_lshl_add_u64 v[118:119], v[30:31], 0, v[118:119]
	v_lshl_add_u64 v[124:125], v[30:31], 0, v[124:125]
	v_lshl_add_u64 v[122:123], v[30:31], 0, v[122:123]
	v_lshl_add_u64 v[128:129], v[30:31], 0, v[128:129]
	v_lshl_add_u64 v[126:127], v[30:31], 0, v[126:127]
	global_load_dword v143, v[100:101], off
	global_load_dword v144, v[98:99], off
	global_load_dword v145, v[104:105], off
	global_load_dword v146, v[102:103], off
	global_load_dword v147, v[108:109], off
	global_load_dword v148, v[106:107], off
	global_load_dword v149, v[112:113], off
	global_load_dword v150, v[110:111], off
	global_load_dword v151, v[116:117], off
	global_load_dword v152, v[114:115], off
	global_load_dword v153, v[120:121], off
	global_load_dword v154, v[118:119], off
	global_load_dword v155, v[124:125], off
	global_load_dword v156, v[122:123], off
	global_load_dword v157, v[128:129], off
	global_load_dword v158, v[126:127], off
	v_mad_u64_u32 v[36:37], s[16:17], v27, s10, v[6:7]
	v_mad_u64_u32 v[38:39], s[16:17], v2, s10, v[6:7]
	v_mad_u64_u32 v[40:41], s[16:17], v68, s10, v[6:7]
	v_mad_u64_u32 v[42:43], s[16:17], v29, s10, v[6:7]
	v_mad_u64_u32 v[44:45], s[16:17], v70, s10, v[6:7]
	v_mad_u64_u32 v[46:47], s[16:17], v69, s10, v[6:7]
	v_mad_u64_u32 v[48:49], s[16:17], v72, s10, v[6:7]
	v_mad_u64_u32 v[50:51], s[16:17], v71, s10, v[6:7]
	v_mad_u64_u32 v[52:53], s[16:17], v74, s10, v[6:7]
	v_mad_u64_u32 v[54:55], s[16:17], v73, s10, v[6:7]
	v_mad_u64_u32 v[56:57], s[16:17], v76, s10, v[6:7]
	v_mad_u64_u32 v[58:59], s[16:17], v75, s10, v[6:7]
	v_mad_u64_u32 v[60:61], s[16:17], v78, s10, v[6:7]
	v_mad_u64_u32 v[62:63], s[16:17], v77, s10, v[6:7]
	v_mad_u64_u32 v[64:65], s[16:17], v80, s10, v[6:7]
	v_mad_u64_u32 v[66:67], s[16:17], v79, s10, v[6:7]
	s_waitcnt vmcnt(31)
	ds_write_b32 v36, v81
	s_waitcnt vmcnt(30)
	ds_write_b32 v38, v82
	s_waitcnt vmcnt(29)
	ds_write_b32 v40, v83
	s_waitcnt vmcnt(28)
	ds_write_b32 v42, v84
	s_waitcnt vmcnt(27)
	ds_write_b32 v44, v85
	s_waitcnt vmcnt(26)
	ds_write_b32 v46, v86
	s_waitcnt vmcnt(25)
	ds_write_b32 v48, v87
	s_waitcnt vmcnt(24)
	ds_write_b32 v50, v88
	s_waitcnt vmcnt(23)
	ds_write_b32 v52, v89
	s_waitcnt vmcnt(22)
	ds_write_b32 v54, v90
	s_waitcnt vmcnt(21)
	ds_write_b32 v56, v91
	s_waitcnt vmcnt(20)
	ds_write_b32 v58, v92
	s_waitcnt vmcnt(19)
	ds_write_b32 v60, v93
	s_waitcnt vmcnt(18)
	ds_write_b32 v62, v94
	s_waitcnt vmcnt(17)
	ds_write_b32 v64, v95
	s_waitcnt vmcnt(16)
	ds_write_b32 v66, v96
	v_mad_u64_u32 v[98:99], s[16:17], v161, s10, v[6:7]
	v_mad_u64_u32 v[100:101], s[16:17], v160, s10, v[6:7]
	v_mad_u64_u32 v[102:103], s[16:17], v130, s10, v[6:7]
	v_mad_u64_u32 v[104:105], s[16:17], v162, s10, v[6:7]
	v_mad_u64_u32 v[106:107], s[16:17], v132, s10, v[6:7]
	v_mad_u64_u32 v[108:109], s[16:17], v131, s10, v[6:7]
	v_mad_u64_u32 v[110:111], s[16:17], v134, s10, v[6:7]
	v_mad_u64_u32 v[112:113], s[16:17], v133, s10, v[6:7]
	v_mad_u64_u32 v[114:115], s[16:17], v136, s10, v[6:7]
	v_mad_u64_u32 v[116:117], s[16:17], v135, s10, v[6:7]
	v_mad_u64_u32 v[118:119], s[16:17], v138, s10, v[6:7]
	v_mad_u64_u32 v[120:121], s[16:17], v137, s10, v[6:7]
	v_mad_u64_u32 v[122:123], s[16:17], v140, s10, v[6:7]
	v_mad_u64_u32 v[124:125], s[16:17], v139, s10, v[6:7]
	v_mad_u64_u32 v[126:127], s[16:17], v142, s10, v[6:7]
	v_mad_u64_u32 v[128:129], s[16:17], v141, s10, v[6:7]
	s_waitcnt vmcnt(15)
	ds_write_b32 v98, v143
	s_waitcnt vmcnt(14)
	ds_write_b32 v100, v144
	s_waitcnt vmcnt(13)
	ds_write_b32 v102, v145
	s_waitcnt vmcnt(12)
	ds_write_b32 v104, v146
	s_waitcnt vmcnt(11)
	ds_write_b32 v106, v147
	s_waitcnt vmcnt(10)
	ds_write_b32 v108, v148
	s_waitcnt vmcnt(9)
	ds_write_b32 v110, v149
	s_waitcnt vmcnt(8)
	ds_write_b32 v112, v150
	s_waitcnt vmcnt(7)
	ds_write_b32 v114, v151
	s_waitcnt vmcnt(6)
	ds_write_b32 v116, v152
	s_waitcnt vmcnt(5)
	ds_write_b32 v118, v153
	s_waitcnt vmcnt(4)
	ds_write_b32 v120, v154
	s_waitcnt vmcnt(3)
	ds_write_b32 v122, v155
	s_waitcnt vmcnt(2)
	ds_write_b32 v124, v156
	s_waitcnt vmcnt(1)
	ds_write_b32 v126, v157
	s_waitcnt vmcnt(0)
	ds_write_b32 v128, v158
	s_add_i32 s11, s11, 16
	s_add_i32 s7, s7, 16
	s_add_i32 s15, s15, -16
	s_add_i32 s15, s15, -16
	s_cmp_lg_u32 s15, 0
	s_waitcnt lgkmcnt(0)
	ds_read2_b32 v[30:31], v32 offset1:33
	s_waitcnt lgkmcnt(0)
	v_cvt_pk_bf16_f32 v36, v30, v31
	ds_read2_b32 v[30:31], v32 offset0:66 offset1:99
	v_or_b32_e32 v40, s2, v7
	s_waitcnt lgkmcnt(0)
	v_cvt_pk_bf16_f32 v37, v30, v31
	ds_read2_b32 v[30:31], v32 offset0:132 offset1:165
	s_ashr_i32 s7, s6, 31
	v_ashrrev_i32_e32 v41, 31, v40
	s_waitcnt lgkmcnt(0)
	v_cvt_pk_bf16_f32 v38, v30, v31
	ds_read2_b32 v[30:31], v32 offset0:198 offset1:231
	v_lshl_add_u64 v[42:43], s[6:7], 1, v[16:17]
	v_lshlrev_b64 v[40:41], 11, v[40:41]
	s_waitcnt lgkmcnt(0)
	v_cvt_pk_bf16_f32 v39, v30, v31
	ds_read2_b32 v[30:31], v32 offset0:8 offset1:41
	v_lshl_add_u64 v[40:41], v[42:43], 0, v[40:41]
	global_store_dwordx4 v[40:41], v[36:39], off
	v_or_b32_e32 v40, s2, v33
	v_ashrrev_i32_e32 v41, 31, v40
	s_waitcnt lgkmcnt(0)
	v_cvt_pk_bf16_f32 v36, v30, v31
	ds_read2_b32 v[30:31], v32 offset0:74 offset1:107
	s_waitcnt lgkmcnt(0)
	v_cvt_pk_bf16_f32 v37, v30, v31
	ds_read2_b32 v[30:31], v32 offset0:140 offset1:173
	s_waitcnt lgkmcnt(0)
	v_cvt_pk_bf16_f32 v38, v30, v31
	ds_read2_b32 v[30:31], v32 offset0:206 offset1:239
	v_lshlrev_b64 v[40:41], 11, v[40:41]
	s_waitcnt lgkmcnt(0)
	v_cvt_pk_bf16_f32 v39, v30, v31
	ds_read2_b32 v[30:31], v32 offset0:16 offset1:49
	v_lshl_add_u64 v[40:41], v[42:43], 0, v[40:41]
	global_store_dwordx4 v[40:41], v[36:39], off
	v_or_b32_e32 v40, s2, v34
	v_ashrrev_i32_e32 v41, 31, v40
	s_waitcnt lgkmcnt(0)
	v_cvt_pk_bf16_f32 v36, v30, v31
	ds_read2_b32 v[30:31], v32 offset0:82 offset1:115
	s_waitcnt lgkmcnt(0)
	v_cvt_pk_bf16_f32 v37, v30, v31
	ds_read2_b32 v[30:31], v32 offset0:148 offset1:181
	s_waitcnt lgkmcnt(0)
	v_cvt_pk_bf16_f32 v38, v30, v31
	ds_read2_b32 v[30:31], v32 offset0:214 offset1:247
	v_lshlrev_b64 v[40:41], 11, v[40:41]
	s_waitcnt lgkmcnt(0)
	v_cvt_pk_bf16_f32 v39, v30, v31
	ds_read2_b32 v[30:31], v32 offset0:24 offset1:57
	v_lshl_add_u64 v[40:41], v[42:43], 0, v[40:41]
	global_store_dwordx4 v[40:41], v[36:39], off
	v_or_b32_e32 v40, s2, v35
	v_ashrrev_i32_e32 v41, 31, v40
	s_waitcnt lgkmcnt(0)
	v_cvt_pk_bf16_f32 v36, v30, v31
	ds_read2_b32 v[30:31], v32 offset0:90 offset1:123
	s_waitcnt lgkmcnt(0)
	v_cvt_pk_bf16_f32 v37, v30, v31
	ds_read2_b32 v[30:31], v32 offset0:156 offset1:189
	s_waitcnt lgkmcnt(0)
	v_cvt_pk_bf16_f32 v38, v30, v31
	ds_read2_b32 v[30:31], v32 offset0:222 offset1:255
	v_lshlrev_b64 v[40:41], 11, v[40:41]
	s_waitcnt lgkmcnt(0)
	v_cvt_pk_bf16_f32 v39, v30, v31
	v_lshl_add_u64 v[30:31], v[42:43], 0, v[40:41]
	global_store_dwordx4 v[30:31], v[36:39], off
	s_waitcnt lgkmcnt(0)
	s_mov_b32 s11, s14
	s_andn2_b64 vcc, exec, s[0:1]
	s_cbranch_vccnz .LBB0_335

.LBB0_362:
	s_lshl_b32 s16, s7, 1
	s_lshl_b32 s17, s14, 1
	v_or_b32_e32 v2, s16, v1
	v_or_b32_e32 v27, s17, v0
	s_add_i32 s18, s16, 4
	s_add_i32 s19, s17, 4
	s_add_i32 s20, s16, 8
	s_add_i32 s21, s17, 8
	s_add_i32 s22, s16, 12
	s_add_i32 s23, s17, 12
	s_add_i32 s24, s16, 16
	s_add_i32 s25, s17, 16
	s_add_i32 s26, s16, 20
	s_add_i32 s27, s17, 20
	s_add_i32 s28, s16, 24
	s_add_i32 s29, s17, 24
	s_add_i32 s16, s16, 28
	s_add_i32 s17, s17, 28
	v_add_u32_e32 v38, s6, v27
	v_or_b32_e32 v29, s18, v1
	v_or_b32_e32 v68, s19, v0
	v_or_b32_e32 v69, s20, v1
	v_or_b32_e32 v70, s21, v0
	v_or_b32_e32 v71, s22, v1
	v_or_b32_e32 v72, s23, v0
	v_or_b32_e32 v73, s24, v1
	v_or_b32_e32 v74, s25, v0
	v_or_b32_e32 v75, s26, v1
	v_or_b32_e32 v76, s27, v0
	v_or_b32_e32 v77, s28, v1
	v_or_b32_e32 v78, s29, v0
	v_or_b32_e32 v79, s16, v1
	v_or_b32_e32 v80, s17, v0
	v_add_u32_e32 v36, s3, v2
	v_ashrrev_i32_e32 v39, 31, v38
	v_add_u32_e32 v40, s3, v29
	v_add_u32_e32 v42, s6, v68
	v_add_u32_e32 v44, s3, v69
	v_add_u32_e32 v46, s6, v70
	v_add_u32_e32 v48, s3, v71
	v_add_u32_e32 v50, s6, v72
	v_add_u32_e32 v52, s3, v73
	v_add_u32_e32 v54, s6, v74
	v_add_u32_e32 v56, s3, v75
	v_add_u32_e32 v58, s6, v76
	v_add_u32_e32 v60, s3, v77
	v_add_u32_e32 v62, s6, v78
	v_add_u32_e32 v64, s3, v79
	v_add_u32_e32 v66, s6, v80
	v_ashrrev_i32_e32 v37, 31, v36
	v_lshlrev_b64 v[38:39], 13, v[38:39]
	v_ashrrev_i32_e32 v43, 31, v42
	v_ashrrev_i32_e32 v41, 31, v40
	v_ashrrev_i32_e32 v47, 31, v46
	v_ashrrev_i32_e32 v45, 31, v44
	v_ashrrev_i32_e32 v51, 31, v50
	v_ashrrev_i32_e32 v49, 31, v48
	v_ashrrev_i32_e32 v55, 31, v54
	v_ashrrev_i32_e32 v53, 31, v52
	v_ashrrev_i32_e32 v59, 31, v58
	v_ashrrev_i32_e32 v57, 31, v56
	v_ashrrev_i32_e32 v63, 31, v62
	v_ashrrev_i32_e32 v61, 31, v60
	v_ashrrev_i32_e32 v67, 31, v66
	v_ashrrev_i32_e32 v65, 31, v64
	v_lshlrev_b64 v[36:37], 13, v[36:37]
	v_lshl_add_u64 v[38:39], v[30:31], 0, v[38:39]
	v_lshlrev_b64 v[40:41], 13, v[40:41]
	v_lshlrev_b64 v[42:43], 13, v[42:43]
	v_lshlrev_b64 v[44:45], 13, v[44:45]
	v_lshlrev_b64 v[46:47], 13, v[46:47]
	v_lshlrev_b64 v[48:49], 13, v[48:49]
	v_lshlrev_b64 v[50:51], 13, v[50:51]
	v_lshlrev_b64 v[52:53], 13, v[52:53]
	v_lshlrev_b64 v[54:55], 13, v[54:55]
	v_lshlrev_b64 v[56:57], 13, v[56:57]
	v_lshlrev_b64 v[58:59], 13, v[58:59]
	v_lshlrev_b64 v[60:61], 13, v[60:61]
	v_lshlrev_b64 v[62:63], 13, v[62:63]
	v_lshlrev_b64 v[64:65], 13, v[64:65]
	v_lshlrev_b64 v[66:67], 13, v[66:67]
	v_lshl_add_u64 v[36:37], v[30:31], 0, v[36:37]
	v_lshl_add_u64 v[42:43], v[30:31], 0, v[42:43]
	v_lshl_add_u64 v[40:41], v[30:31], 0, v[40:41]
	v_lshl_add_u64 v[46:47], v[30:31], 0, v[46:47]
	v_lshl_add_u64 v[44:45], v[30:31], 0, v[44:45]
	v_lshl_add_u64 v[50:51], v[30:31], 0, v[50:51]
	v_lshl_add_u64 v[48:49], v[30:31], 0, v[48:49]
	v_lshl_add_u64 v[54:55], v[30:31], 0, v[54:55]
	v_lshl_add_u64 v[52:53], v[30:31], 0, v[52:53]
	v_lshl_add_u64 v[58:59], v[30:31], 0, v[58:59]
	v_lshl_add_u64 v[56:57], v[30:31], 0, v[56:57]
	v_lshl_add_u64 v[62:63], v[30:31], 0, v[62:63]
	v_lshl_add_u64 v[60:61], v[30:31], 0, v[60:61]
	v_lshl_add_u64 v[66:67], v[30:31], 0, v[66:67]
	v_lshl_add_u64 v[64:65], v[30:31], 0, v[64:65]
	global_load_dword v81, v[38:39], off
	global_load_dword v82, v[36:37], off
	global_load_dword v83, v[42:43], off
	global_load_dword v84, v[40:41], off
	global_load_dword v85, v[46:47], off
	global_load_dword v86, v[44:45], off
	global_load_dword v87, v[50:51], off
	global_load_dword v88, v[48:49], off
	global_load_dword v89, v[54:55], off
	global_load_dword v90, v[52:53], off
	global_load_dword v91, v[58:59], off
	global_load_dword v92, v[56:57], off
	global_load_dword v93, v[62:63], off
	global_load_dword v94, v[60:61], off
	global_load_dword v95, v[66:67], off
	global_load_dword v96, v[64:65], off
	s_add_i32 s14, s14, 16
	s_add_i32 s7, s7, 16
	s_lshl_b32 s16, s7, 1
	s_lshl_b32 s17, s14, 1
	v_or_b32_e32 v160, s16, v1
	v_or_b32_e32 v161, s17, v0
	s_add_i32 s18, s16, 4
	s_add_i32 s19, s17, 4
	s_add_i32 s20, s16, 8
	s_add_i32 s21, s17, 8
	s_add_i32 s22, s16, 12
	s_add_i32 s23, s17, 12
	s_add_i32 s24, s16, 16
	s_add_i32 s25, s17, 16
	s_add_i32 s26, s16, 20
	s_add_i32 s27, s17, 20
	s_add_i32 s28, s16, 24
	s_add_i32 s29, s17, 24
	s_add_i32 s16, s16, 28
	s_add_i32 s17, s17, 28
	v_add_u32_e32 v100, s6, v161
	v_or_b32_e32 v162, s18, v1
	v_or_b32_e32 v130, s19, v0
	v_or_b32_e32 v131, s20, v1
	v_or_b32_e32 v132, s21, v0
	v_or_b32_e32 v133, s22, v1
	v_or_b32_e32 v134, s23, v0
	v_or_b32_e32 v135, s24, v1
	v_or_b32_e32 v136, s25, v0
	v_or_b32_e32 v137, s26, v1
	v_or_b32_e32 v138, s27, v0
	v_or_b32_e32 v139, s28, v1
	v_or_b32_e32 v140, s29, v0
	v_or_b32_e32 v141, s16, v1
	v_or_b32_e32 v142, s17, v0
	v_add_u32_e32 v98, s3, v160
	v_ashrrev_i32_e32 v101, 31, v100
	v_add_u32_e32 v102, s3, v162
	v_add_u32_e32 v104, s6, v130
	v_add_u32_e32 v106, s3, v131
	v_add_u32_e32 v108, s6, v132
	v_add_u32_e32 v110, s3, v133
	v_add_u32_e32 v112, s6, v134
	v_add_u32_e32 v114, s3, v135
	v_add_u32_e32 v116, s6, v136
	v_add_u32_e32 v118, s3, v137
	v_add_u32_e32 v120, s6, v138
	v_add_u32_e32 v122, s3, v139
	v_add_u32_e32 v124, s6, v140
	v_add_u32_e32 v126, s3, v141
	v_add_u32_e32 v128, s6, v142
	v_ashrrev_i32_e32 v99, 31, v98
	v_lshlrev_b64 v[100:101], 13, v[100:101]
	v_ashrrev_i32_e32 v105, 31, v104
	v_ashrrev_i32_e32 v103, 31, v102
	v_ashrrev_i32_e32 v109, 31, v108
	v_ashrrev_i32_e32 v107, 31, v106
	v_ashrrev_i32_e32 v113, 31, v112
	v_ashrrev_i32_e32 v111, 31, v110
	v_ashrrev_i32_e32 v117, 31, v116
	v_ashrrev_i32_e32 v115, 31, v114
	v_ashrrev_i32_e32 v121, 31, v120
	v_ashrrev_i32_e32 v119, 31, v118
	v_ashrrev_i32_e32 v125, 31, v124
	v_ashrrev_i32_e32 v123, 31, v122
	v_ashrrev_i32_e32 v129, 31, v128
	v_ashrrev_i32_e32 v127, 31, v126
	v_lshlrev_b64 v[98:99], 13, v[98:99]
	v_lshl_add_u64 v[100:101], v[30:31], 0, v[100:101]
	v_lshlrev_b64 v[102:103], 13, v[102:103]
	v_lshlrev_b64 v[104:105], 13, v[104:105]
	v_lshlrev_b64 v[106:107], 13, v[106:107]
	v_lshlrev_b64 v[108:109], 13, v[108:109]
	v_lshlrev_b64 v[110:111], 13, v[110:111]
	v_lshlrev_b64 v[112:113], 13, v[112:113]
	v_lshlrev_b64 v[114:115], 13, v[114:115]
	v_lshlrev_b64 v[116:117], 13, v[116:117]
	v_lshlrev_b64 v[118:119], 13, v[118:119]
	v_lshlrev_b64 v[120:121], 13, v[120:121]
	v_lshlrev_b64 v[122:123], 13, v[122:123]
	v_lshlrev_b64 v[124:125], 13, v[124:125]
	v_lshlrev_b64 v[126:127], 13, v[126:127]
	v_lshlrev_b64 v[128:129], 13, v[128:129]
	v_lshl_add_u64 v[98:99], v[30:31], 0, v[98:99]
	v_lshl_add_u64 v[104:105], v[30:31], 0, v[104:105]
	v_lshl_add_u64 v[102:103], v[30:31], 0, v[102:103]
	v_lshl_add_u64 v[108:109], v[30:31], 0, v[108:109]
	v_lshl_add_u64 v[106:107], v[30:31], 0, v[106:107]
	v_lshl_add_u64 v[112:113], v[30:31], 0, v[112:113]
	v_lshl_add_u64 v[110:111], v[30:31], 0, v[110:111]
	v_lshl_add_u64 v[116:117], v[30:31], 0, v[116:117]
	v_lshl_add_u64 v[114:115], v[30:31], 0, v[114:115]
	v_lshl_add_u64 v[120:121], v[30:31], 0, v[120:121]
	v_lshl_add_u64 v[118:119], v[30:31], 0, v[118:119]
	v_lshl_add_u64 v[124:125], v[30:31], 0, v[124:125]
	v_lshl_add_u64 v[122:123], v[30:31], 0, v[122:123]
	v_lshl_add_u64 v[128:129], v[30:31], 0, v[128:129]
	v_lshl_add_u64 v[126:127], v[30:31], 0, v[126:127]
	global_load_dword v143, v[100:101], off
	global_load_dword v144, v[98:99], off
	global_load_dword v145, v[104:105], off
	global_load_dword v146, v[102:103], off
	global_load_dword v147, v[108:109], off
	global_load_dword v148, v[106:107], off
	global_load_dword v149, v[112:113], off
	global_load_dword v150, v[110:111], off
	global_load_dword v151, v[116:117], off
	global_load_dword v152, v[114:115], off
	global_load_dword v153, v[120:121], off
	global_load_dword v154, v[118:119], off
	global_load_dword v155, v[124:125], off
	global_load_dword v156, v[122:123], off
	global_load_dword v157, v[128:129], off
	global_load_dword v158, v[126:127], off
	v_mad_u64_u32 v[36:37], s[16:17], v27, s10, v[6:7]
	v_mad_u64_u32 v[38:39], s[16:17], v2, s10, v[6:7]
	v_mad_u64_u32 v[40:41], s[16:17], v68, s10, v[6:7]
	v_mad_u64_u32 v[42:43], s[16:17], v29, s10, v[6:7]
	v_mad_u64_u32 v[44:45], s[16:17], v70, s10, v[6:7]
	v_mad_u64_u32 v[46:47], s[16:17], v69, s10, v[6:7]
	v_mad_u64_u32 v[48:49], s[16:17], v72, s10, v[6:7]
	v_mad_u64_u32 v[50:51], s[16:17], v71, s10, v[6:7]
	v_mad_u64_u32 v[52:53], s[16:17], v74, s10, v[6:7]
	v_mad_u64_u32 v[54:55], s[16:17], v73, s10, v[6:7]
	v_mad_u64_u32 v[56:57], s[16:17], v76, s10, v[6:7]
	v_mad_u64_u32 v[58:59], s[16:17], v75, s10, v[6:7]
	v_mad_u64_u32 v[60:61], s[16:17], v78, s10, v[6:7]
	v_mad_u64_u32 v[62:63], s[16:17], v77, s10, v[6:7]
	v_mad_u64_u32 v[64:65], s[16:17], v80, s10, v[6:7]
	v_mad_u64_u32 v[66:67], s[16:17], v79, s10, v[6:7]
	s_waitcnt vmcnt(31)
	ds_write_b32 v36, v81
	s_waitcnt vmcnt(30)
	ds_write_b32 v38, v82
	s_waitcnt vmcnt(29)
	ds_write_b32 v40, v83
	s_waitcnt vmcnt(28)
	ds_write_b32 v42, v84
	s_waitcnt vmcnt(27)
	ds_write_b32 v44, v85
	s_waitcnt vmcnt(26)
	ds_write_b32 v46, v86
	s_waitcnt vmcnt(25)
	ds_write_b32 v48, v87
	s_waitcnt vmcnt(24)
	ds_write_b32 v50, v88
	s_waitcnt vmcnt(23)
	ds_write_b32 v52, v89
	s_waitcnt vmcnt(22)
	ds_write_b32 v54, v90
	s_waitcnt vmcnt(21)
	ds_write_b32 v56, v91
	s_waitcnt vmcnt(20)
	ds_write_b32 v58, v92
	s_waitcnt vmcnt(19)
	ds_write_b32 v60, v93
	s_waitcnt vmcnt(18)
	ds_write_b32 v62, v94
	s_waitcnt vmcnt(17)
	ds_write_b32 v64, v95
	s_waitcnt vmcnt(16)
	ds_write_b32 v66, v96
	v_mad_u64_u32 v[98:99], s[16:17], v161, s10, v[6:7]
	v_mad_u64_u32 v[100:101], s[16:17], v160, s10, v[6:7]
	v_mad_u64_u32 v[102:103], s[16:17], v130, s10, v[6:7]
	v_mad_u64_u32 v[104:105], s[16:17], v162, s10, v[6:7]
	v_mad_u64_u32 v[106:107], s[16:17], v132, s10, v[6:7]
	v_mad_u64_u32 v[108:109], s[16:17], v131, s10, v[6:7]
	v_mad_u64_u32 v[110:111], s[16:17], v134, s10, v[6:7]
	v_mad_u64_u32 v[112:113], s[16:17], v133, s10, v[6:7]
	v_mad_u64_u32 v[114:115], s[16:17], v136, s10, v[6:7]
	v_mad_u64_u32 v[116:117], s[16:17], v135, s10, v[6:7]
	v_mad_u64_u32 v[118:119], s[16:17], v138, s10, v[6:7]
	v_mad_u64_u32 v[120:121], s[16:17], v137, s10, v[6:7]
	v_mad_u64_u32 v[122:123], s[16:17], v140, s10, v[6:7]
	v_mad_u64_u32 v[124:125], s[16:17], v139, s10, v[6:7]
	v_mad_u64_u32 v[126:127], s[16:17], v142, s10, v[6:7]
	v_mad_u64_u32 v[128:129], s[16:17], v141, s10, v[6:7]
	s_waitcnt vmcnt(15)
	ds_write_b32 v98, v143
	s_waitcnt vmcnt(14)
	ds_write_b32 v100, v144
	s_waitcnt vmcnt(13)
	ds_write_b32 v102, v145
	s_waitcnt vmcnt(12)
	ds_write_b32 v104, v146
	s_waitcnt vmcnt(11)
	ds_write_b32 v106, v147
	s_waitcnt vmcnt(10)
	ds_write_b32 v108, v148
	s_waitcnt vmcnt(9)
	ds_write_b32 v110, v149
	s_waitcnt vmcnt(8)
	ds_write_b32 v112, v150
	s_waitcnt vmcnt(7)
	ds_write_b32 v114, v151
	s_waitcnt vmcnt(6)
	ds_write_b32 v116, v152
	s_waitcnt vmcnt(5)
	ds_write_b32 v118, v153
	s_waitcnt vmcnt(4)
	ds_write_b32 v120, v154
	s_waitcnt vmcnt(3)
	ds_write_b32 v122, v155
	s_waitcnt vmcnt(2)
	ds_write_b32 v124, v156
	s_waitcnt vmcnt(1)
	ds_write_b32 v126, v157
	s_waitcnt vmcnt(0)
	ds_write_b32 v128, v158
	s_add_i32 s14, s14, 16
	s_add_i32 s7, s7, 16
	s_add_i32 s15, s15, -16
	s_add_i32 s15, s15, -16
	s_cmp_lg_u32 s15, 0
	s_waitcnt lgkmcnt(0)
	ds_read2_b32 v[30:31], v32 offset1:33
	s_waitcnt lgkmcnt(0)
	v_cvt_pk_bf16_f32 v36, v30, v31
	ds_read2_b32 v[30:31], v32 offset0:66 offset1:99
	v_or_b32_e32 v40, s2, v7
	s_waitcnt lgkmcnt(0)
	v_cvt_pk_bf16_f32 v37, v30, v31
	ds_read2_b32 v[30:31], v32 offset0:132 offset1:165
	s_ashr_i32 s7, s6, 31
	v_ashrrev_i32_e32 v41, 31, v40
	s_waitcnt lgkmcnt(0)
	v_cvt_pk_bf16_f32 v38, v30, v31
	ds_read2_b32 v[30:31], v32 offset0:198 offset1:231
	v_lshl_add_u64 v[42:43], s[6:7], 1, v[20:21]
	v_lshlrev_b64 v[40:41], 11, v[40:41]
	s_waitcnt lgkmcnt(0)
	v_cvt_pk_bf16_f32 v39, v30, v31
	ds_read2_b32 v[30:31], v32 offset0:8 offset1:41
	v_lshl_add_u64 v[40:41], v[42:43], 0, v[40:41]
	global_store_dwordx4 v[40:41], v[36:39], off
	v_or_b32_e32 v40, s2, v33
	v_ashrrev_i32_e32 v41, 31, v40
	s_waitcnt lgkmcnt(0)
	v_cvt_pk_bf16_f32 v36, v30, v31
	ds_read2_b32 v[30:31], v32 offset0:74 offset1:107
	s_waitcnt lgkmcnt(0)
	v_cvt_pk_bf16_f32 v37, v30, v31
	ds_read2_b32 v[30:31], v32 offset0:140 offset1:173
	s_waitcnt lgkmcnt(0)
	v_cvt_pk_bf16_f32 v38, v30, v31
	ds_read2_b32 v[30:31], v32 offset0:206 offset1:239
	v_lshlrev_b64 v[40:41], 11, v[40:41]
	s_waitcnt lgkmcnt(0)
	v_cvt_pk_bf16_f32 v39, v30, v31
	ds_read2_b32 v[30:31], v32 offset0:16 offset1:49
	v_lshl_add_u64 v[40:41], v[42:43], 0, v[40:41]
	global_store_dwordx4 v[40:41], v[36:39], off
	v_or_b32_e32 v40, s2, v34
	v_ashrrev_i32_e32 v41, 31, v40
	s_waitcnt lgkmcnt(0)
	v_cvt_pk_bf16_f32 v36, v30, v31
	ds_read2_b32 v[30:31], v32 offset0:82 offset1:115
	s_waitcnt lgkmcnt(0)
	v_cvt_pk_bf16_f32 v37, v30, v31
	ds_read2_b32 v[30:31], v32 offset0:148 offset1:181
	s_waitcnt lgkmcnt(0)
	v_cvt_pk_bf16_f32 v38, v30, v31
	ds_read2_b32 v[30:31], v32 offset0:214 offset1:247
	v_lshlrev_b64 v[40:41], 11, v[40:41]
	s_waitcnt lgkmcnt(0)
	v_cvt_pk_bf16_f32 v39, v30, v31
	ds_read2_b32 v[30:31], v32 offset0:24 offset1:57
	v_lshl_add_u64 v[40:41], v[42:43], 0, v[40:41]
	global_store_dwordx4 v[40:41], v[36:39], off
	v_or_b32_e32 v40, s2, v35
	v_ashrrev_i32_e32 v41, 31, v40
	s_waitcnt lgkmcnt(0)
	v_cvt_pk_bf16_f32 v36, v30, v31
	ds_read2_b32 v[30:31], v32 offset0:90 offset1:123
	s_waitcnt lgkmcnt(0)
	v_cvt_pk_bf16_f32 v37, v30, v31
	ds_read2_b32 v[30:31], v32 offset0:156 offset1:189
	s_waitcnt lgkmcnt(0)
	v_cvt_pk_bf16_f32 v38, v30, v31
	ds_read2_b32 v[30:31], v32 offset0:222 offset1:255
	v_lshlrev_b64 v[40:41], 11, v[40:41]
	s_waitcnt lgkmcnt(0)
	v_cvt_pk_bf16_f32 v39, v30, v31
	v_lshl_add_u64 v[30:31], v[42:43], 0, v[40:41]
	global_store_dwordx4 v[30:31], v[36:39], off
	s_waitcnt lgkmcnt(0)
	s_mov_b32 s14, s11
	s_andn2_b64 vcc, exec, s[0:1]
	s_cbranch_vccnz .LBB0_335

.LBB0_369:
	s_lshl_b32 s16, s7, 1
	s_lshl_b32 s17, s11, 1
	v_or_b32_e32 v2, s16, v1
	v_or_b32_e32 v27, s17, v0
	s_add_i32 s18, s16, 4
	s_add_i32 s19, s17, 4
	s_add_i32 s20, s16, 8
	s_add_i32 s21, s17, 8
	s_add_i32 s22, s16, 12
	s_add_i32 s23, s17, 12
	s_add_i32 s24, s16, 16
	s_add_i32 s25, s17, 16
	s_add_i32 s26, s16, 20
	s_add_i32 s27, s17, 20
	s_add_i32 s28, s16, 24
	s_add_i32 s29, s17, 24
	s_add_i32 s16, s16, 28
	s_add_i32 s17, s17, 28
	v_add_u32_e32 v38, s6, v27
	v_or_b32_e32 v29, s18, v1
	v_or_b32_e32 v68, s19, v0
	v_or_b32_e32 v69, s20, v1
	v_or_b32_e32 v70, s21, v0
	v_or_b32_e32 v71, s22, v1
	v_or_b32_e32 v72, s23, v0
	v_or_b32_e32 v73, s24, v1
	v_or_b32_e32 v74, s25, v0
	v_or_b32_e32 v75, s26, v1
	v_or_b32_e32 v76, s27, v0
	v_or_b32_e32 v77, s28, v1
	v_or_b32_e32 v78, s29, v0
	v_or_b32_e32 v79, s16, v1
	v_or_b32_e32 v80, s17, v0
	v_add_u32_e32 v36, s3, v2
	v_ashrrev_i32_e32 v39, 31, v38
	v_add_u32_e32 v40, s3, v29
	v_add_u32_e32 v42, s6, v68
	v_add_u32_e32 v44, s3, v69
	v_add_u32_e32 v46, s6, v70
	v_add_u32_e32 v48, s3, v71
	v_add_u32_e32 v50, s6, v72
	v_add_u32_e32 v52, s3, v73
	v_add_u32_e32 v54, s6, v74
	v_add_u32_e32 v56, s3, v75
	v_add_u32_e32 v58, s6, v76
	v_add_u32_e32 v60, s3, v77
	v_add_u32_e32 v62, s6, v78
	v_add_u32_e32 v64, s3, v79
	v_add_u32_e32 v66, s6, v80
	v_ashrrev_i32_e32 v37, 31, v36
	v_lshlrev_b64 v[38:39], 13, v[38:39]
	v_ashrrev_i32_e32 v43, 31, v42
	v_ashrrev_i32_e32 v41, 31, v40
	v_ashrrev_i32_e32 v47, 31, v46
	v_ashrrev_i32_e32 v45, 31, v44
	v_ashrrev_i32_e32 v51, 31, v50
	v_ashrrev_i32_e32 v49, 31, v48
	v_ashrrev_i32_e32 v55, 31, v54
	v_ashrrev_i32_e32 v53, 31, v52
	v_ashrrev_i32_e32 v59, 31, v58
	v_ashrrev_i32_e32 v57, 31, v56
	v_ashrrev_i32_e32 v63, 31, v62
	v_ashrrev_i32_e32 v61, 31, v60
	v_ashrrev_i32_e32 v67, 31, v66
	v_ashrrev_i32_e32 v65, 31, v64
	v_lshlrev_b64 v[36:37], 13, v[36:37]
	v_lshl_add_u64 v[38:39], v[30:31], 0, v[38:39]
	v_lshlrev_b64 v[40:41], 13, v[40:41]
	v_lshlrev_b64 v[42:43], 13, v[42:43]
	v_lshlrev_b64 v[44:45], 13, v[44:45]
	v_lshlrev_b64 v[46:47], 13, v[46:47]
	v_lshlrev_b64 v[48:49], 13, v[48:49]
	v_lshlrev_b64 v[50:51], 13, v[50:51]
	v_lshlrev_b64 v[52:53], 13, v[52:53]
	v_lshlrev_b64 v[54:55], 13, v[54:55]
	v_lshlrev_b64 v[56:57], 13, v[56:57]
	v_lshlrev_b64 v[58:59], 13, v[58:59]
	v_lshlrev_b64 v[60:61], 13, v[60:61]
	v_lshlrev_b64 v[62:63], 13, v[62:63]
	v_lshlrev_b64 v[64:65], 13, v[64:65]
	v_lshlrev_b64 v[66:67], 13, v[66:67]
	v_lshl_add_u64 v[36:37], v[30:31], 0, v[36:37]
	v_lshl_add_u64 v[42:43], v[30:31], 0, v[42:43]
	v_lshl_add_u64 v[40:41], v[30:31], 0, v[40:41]
	v_lshl_add_u64 v[46:47], v[30:31], 0, v[46:47]
	v_lshl_add_u64 v[44:45], v[30:31], 0, v[44:45]
	v_lshl_add_u64 v[50:51], v[30:31], 0, v[50:51]
	v_lshl_add_u64 v[48:49], v[30:31], 0, v[48:49]
	v_lshl_add_u64 v[54:55], v[30:31], 0, v[54:55]
	v_lshl_add_u64 v[52:53], v[30:31], 0, v[52:53]
	v_lshl_add_u64 v[58:59], v[30:31], 0, v[58:59]
	v_lshl_add_u64 v[56:57], v[30:31], 0, v[56:57]
	v_lshl_add_u64 v[62:63], v[30:31], 0, v[62:63]
	v_lshl_add_u64 v[60:61], v[30:31], 0, v[60:61]
	v_lshl_add_u64 v[66:67], v[30:31], 0, v[66:67]
	v_lshl_add_u64 v[64:65], v[30:31], 0, v[64:65]
	global_load_dword v81, v[38:39], off
	global_load_dword v82, v[36:37], off
	global_load_dword v83, v[42:43], off
	global_load_dword v84, v[40:41], off
	global_load_dword v85, v[46:47], off
	global_load_dword v86, v[44:45], off
	global_load_dword v87, v[50:51], off
	global_load_dword v88, v[48:49], off
	global_load_dword v89, v[54:55], off
	global_load_dword v90, v[52:53], off
	global_load_dword v91, v[58:59], off
	global_load_dword v92, v[56:57], off
	global_load_dword v93, v[62:63], off
	global_load_dword v94, v[60:61], off
	global_load_dword v95, v[66:67], off
	global_load_dword v96, v[64:65], off
	s_add_i32 s11, s11, 16
	s_add_i32 s7, s7, 16
	s_lshl_b32 s16, s7, 1
	s_lshl_b32 s17, s11, 1
	v_or_b32_e32 v160, s16, v1
	v_or_b32_e32 v161, s17, v0
	s_add_i32 s18, s16, 4
	s_add_i32 s19, s17, 4
	s_add_i32 s20, s16, 8
	s_add_i32 s21, s17, 8
	s_add_i32 s22, s16, 12
	s_add_i32 s23, s17, 12
	s_add_i32 s24, s16, 16
	s_add_i32 s25, s17, 16
	s_add_i32 s26, s16, 20
	s_add_i32 s27, s17, 20
	s_add_i32 s28, s16, 24
	s_add_i32 s29, s17, 24
	s_add_i32 s16, s16, 28
	s_add_i32 s17, s17, 28
	v_add_u32_e32 v100, s6, v161
	v_or_b32_e32 v162, s18, v1
	v_or_b32_e32 v130, s19, v0
	v_or_b32_e32 v131, s20, v1
	v_or_b32_e32 v132, s21, v0
	v_or_b32_e32 v133, s22, v1
	v_or_b32_e32 v134, s23, v0
	v_or_b32_e32 v135, s24, v1
	v_or_b32_e32 v136, s25, v0
	v_or_b32_e32 v137, s26, v1
	v_or_b32_e32 v138, s27, v0
	v_or_b32_e32 v139, s28, v1
	v_or_b32_e32 v140, s29, v0
	v_or_b32_e32 v141, s16, v1
	v_or_b32_e32 v142, s17, v0
	v_add_u32_e32 v98, s3, v160
	v_ashrrev_i32_e32 v101, 31, v100
	v_add_u32_e32 v102, s3, v162
	v_add_u32_e32 v104, s6, v130
	v_add_u32_e32 v106, s3, v131
	v_add_u32_e32 v108, s6, v132
	v_add_u32_e32 v110, s3, v133
	v_add_u32_e32 v112, s6, v134
	v_add_u32_e32 v114, s3, v135
	v_add_u32_e32 v116, s6, v136
	v_add_u32_e32 v118, s3, v137
	v_add_u32_e32 v120, s6, v138
	v_add_u32_e32 v122, s3, v139
	v_add_u32_e32 v124, s6, v140
	v_add_u32_e32 v126, s3, v141
	v_add_u32_e32 v128, s6, v142
	v_ashrrev_i32_e32 v99, 31, v98
	v_lshlrev_b64 v[100:101], 13, v[100:101]
	v_ashrrev_i32_e32 v105, 31, v104
	v_ashrrev_i32_e32 v103, 31, v102
	v_ashrrev_i32_e32 v109, 31, v108
	v_ashrrev_i32_e32 v107, 31, v106
	v_ashrrev_i32_e32 v113, 31, v112
	v_ashrrev_i32_e32 v111, 31, v110
	v_ashrrev_i32_e32 v117, 31, v116
	v_ashrrev_i32_e32 v115, 31, v114
	v_ashrrev_i32_e32 v121, 31, v120
	v_ashrrev_i32_e32 v119, 31, v118
	v_ashrrev_i32_e32 v125, 31, v124
	v_ashrrev_i32_e32 v123, 31, v122
	v_ashrrev_i32_e32 v129, 31, v128
	v_ashrrev_i32_e32 v127, 31, v126
	v_lshlrev_b64 v[98:99], 13, v[98:99]
	v_lshl_add_u64 v[100:101], v[30:31], 0, v[100:101]
	v_lshlrev_b64 v[102:103], 13, v[102:103]
	v_lshlrev_b64 v[104:105], 13, v[104:105]
	v_lshlrev_b64 v[106:107], 13, v[106:107]
	v_lshlrev_b64 v[108:109], 13, v[108:109]
	v_lshlrev_b64 v[110:111], 13, v[110:111]
	v_lshlrev_b64 v[112:113], 13, v[112:113]
	v_lshlrev_b64 v[114:115], 13, v[114:115]
	v_lshlrev_b64 v[116:117], 13, v[116:117]
	v_lshlrev_b64 v[118:119], 13, v[118:119]
	v_lshlrev_b64 v[120:121], 13, v[120:121]
	v_lshlrev_b64 v[122:123], 13, v[122:123]
	v_lshlrev_b64 v[124:125], 13, v[124:125]
	v_lshlrev_b64 v[126:127], 13, v[126:127]
	v_lshlrev_b64 v[128:129], 13, v[128:129]
	v_lshl_add_u64 v[98:99], v[30:31], 0, v[98:99]
	v_lshl_add_u64 v[104:105], v[30:31], 0, v[104:105]
	v_lshl_add_u64 v[102:103], v[30:31], 0, v[102:103]
	v_lshl_add_u64 v[108:109], v[30:31], 0, v[108:109]
	v_lshl_add_u64 v[106:107], v[30:31], 0, v[106:107]
	v_lshl_add_u64 v[112:113], v[30:31], 0, v[112:113]
	v_lshl_add_u64 v[110:111], v[30:31], 0, v[110:111]
	v_lshl_add_u64 v[116:117], v[30:31], 0, v[116:117]
	v_lshl_add_u64 v[114:115], v[30:31], 0, v[114:115]
	v_lshl_add_u64 v[120:121], v[30:31], 0, v[120:121]
	v_lshl_add_u64 v[118:119], v[30:31], 0, v[118:119]
	v_lshl_add_u64 v[124:125], v[30:31], 0, v[124:125]
	v_lshl_add_u64 v[122:123], v[30:31], 0, v[122:123]
	v_lshl_add_u64 v[128:129], v[30:31], 0, v[128:129]
	v_lshl_add_u64 v[126:127], v[30:31], 0, v[126:127]
	global_load_dword v143, v[100:101], off
	global_load_dword v144, v[98:99], off
	global_load_dword v145, v[104:105], off
	global_load_dword v146, v[102:103], off
	global_load_dword v147, v[108:109], off
	global_load_dword v148, v[106:107], off
	global_load_dword v149, v[112:113], off
	global_load_dword v150, v[110:111], off
	global_load_dword v151, v[116:117], off
	global_load_dword v152, v[114:115], off
	global_load_dword v153, v[120:121], off
	global_load_dword v154, v[118:119], off
	global_load_dword v155, v[124:125], off
	global_load_dword v156, v[122:123], off
	global_load_dword v157, v[128:129], off
	global_load_dword v158, v[126:127], off
	v_mad_u64_u32 v[36:37], s[16:17], v27, s10, v[6:7]
	v_mad_u64_u32 v[38:39], s[16:17], v2, s10, v[6:7]
	v_mad_u64_u32 v[40:41], s[16:17], v68, s10, v[6:7]
	v_mad_u64_u32 v[42:43], s[16:17], v29, s10, v[6:7]
	v_mad_u64_u32 v[44:45], s[16:17], v70, s10, v[6:7]
	v_mad_u64_u32 v[46:47], s[16:17], v69, s10, v[6:7]
	v_mad_u64_u32 v[48:49], s[16:17], v72, s10, v[6:7]
	v_mad_u64_u32 v[50:51], s[16:17], v71, s10, v[6:7]
	v_mad_u64_u32 v[52:53], s[16:17], v74, s10, v[6:7]
	v_mad_u64_u32 v[54:55], s[16:17], v73, s10, v[6:7]
	v_mad_u64_u32 v[56:57], s[16:17], v76, s10, v[6:7]
	v_mad_u64_u32 v[58:59], s[16:17], v75, s10, v[6:7]
	v_mad_u64_u32 v[60:61], s[16:17], v78, s10, v[6:7]
	v_mad_u64_u32 v[62:63], s[16:17], v77, s10, v[6:7]
	v_mad_u64_u32 v[64:65], s[16:17], v80, s10, v[6:7]
	v_mad_u64_u32 v[66:67], s[16:17], v79, s10, v[6:7]
	s_waitcnt vmcnt(31)
	ds_write_b32 v36, v81
	s_waitcnt vmcnt(30)
	ds_write_b32 v38, v82
	s_waitcnt vmcnt(29)
	ds_write_b32 v40, v83
	s_waitcnt vmcnt(28)
	ds_write_b32 v42, v84
	s_waitcnt vmcnt(27)
	ds_write_b32 v44, v85
	s_waitcnt vmcnt(26)
	ds_write_b32 v46, v86
	s_waitcnt vmcnt(25)
	ds_write_b32 v48, v87
	s_waitcnt vmcnt(24)
	ds_write_b32 v50, v88
	s_waitcnt vmcnt(23)
	ds_write_b32 v52, v89
	s_waitcnt vmcnt(22)
	ds_write_b32 v54, v90
	s_waitcnt vmcnt(21)
	ds_write_b32 v56, v91
	s_waitcnt vmcnt(20)
	ds_write_b32 v58, v92
	s_waitcnt vmcnt(19)
	ds_write_b32 v60, v93
	s_waitcnt vmcnt(18)
	ds_write_b32 v62, v94
	s_waitcnt vmcnt(17)
	ds_write_b32 v64, v95
	s_waitcnt vmcnt(16)
	ds_write_b32 v66, v96
	v_mad_u64_u32 v[98:99], s[16:17], v161, s10, v[6:7]
	v_mad_u64_u32 v[100:101], s[16:17], v160, s10, v[6:7]
	v_mad_u64_u32 v[102:103], s[16:17], v130, s10, v[6:7]
	v_mad_u64_u32 v[104:105], s[16:17], v162, s10, v[6:7]
	v_mad_u64_u32 v[106:107], s[16:17], v132, s10, v[6:7]
	v_mad_u64_u32 v[108:109], s[16:17], v131, s10, v[6:7]
	v_mad_u64_u32 v[110:111], s[16:17], v134, s10, v[6:7]
	v_mad_u64_u32 v[112:113], s[16:17], v133, s10, v[6:7]
	v_mad_u64_u32 v[114:115], s[16:17], v136, s10, v[6:7]
	v_mad_u64_u32 v[116:117], s[16:17], v135, s10, v[6:7]
	v_mad_u64_u32 v[118:119], s[16:17], v138, s10, v[6:7]
	v_mad_u64_u32 v[120:121], s[16:17], v137, s10, v[6:7]
	v_mad_u64_u32 v[122:123], s[16:17], v140, s10, v[6:7]
	v_mad_u64_u32 v[124:125], s[16:17], v139, s10, v[6:7]
	v_mad_u64_u32 v[126:127], s[16:17], v142, s10, v[6:7]
	v_mad_u64_u32 v[128:129], s[16:17], v141, s10, v[6:7]
	s_waitcnt vmcnt(15)
	ds_write_b32 v98, v143
	s_waitcnt vmcnt(14)
	ds_write_b32 v100, v144
	s_waitcnt vmcnt(13)
	ds_write_b32 v102, v145
	s_waitcnt vmcnt(12)
	ds_write_b32 v104, v146
	s_waitcnt vmcnt(11)
	ds_write_b32 v106, v147
	s_waitcnt vmcnt(10)
	ds_write_b32 v108, v148
	s_waitcnt vmcnt(9)
	ds_write_b32 v110, v149
	s_waitcnt vmcnt(8)
	ds_write_b32 v112, v150
	s_waitcnt vmcnt(7)
	ds_write_b32 v114, v151
	s_waitcnt vmcnt(6)
	ds_write_b32 v116, v152
	s_waitcnt vmcnt(5)
	ds_write_b32 v118, v153
	s_waitcnt vmcnt(4)
	ds_write_b32 v120, v154
	s_waitcnt vmcnt(3)
	ds_write_b32 v122, v155
	s_waitcnt vmcnt(2)
	ds_write_b32 v124, v156
	s_waitcnt vmcnt(1)
	ds_write_b32 v126, v157
	s_waitcnt vmcnt(0)
	ds_write_b32 v128, v158
	s_add_i32 s11, s11, 16
	s_add_i32 s7, s7, 16
	s_add_i32 s15, s15, -16
	s_add_i32 s15, s15, -16
	s_cmp_lg_u32 s15, 0
	s_waitcnt lgkmcnt(0)
	ds_read2_b32 v[30:31], v32 offset1:33
	s_waitcnt lgkmcnt(0)
	v_cvt_pk_bf16_f32 v36, v30, v31
	ds_read2_b32 v[30:31], v32 offset0:66 offset1:99
	v_or_b32_e32 v40, s2, v7
	s_waitcnt lgkmcnt(0)
	v_cvt_pk_bf16_f32 v37, v30, v31
	ds_read2_b32 v[30:31], v32 offset0:132 offset1:165
	s_ashr_i32 s7, s6, 31
	v_ashrrev_i32_e32 v41, 31, v40
	s_waitcnt lgkmcnt(0)
	v_cvt_pk_bf16_f32 v38, v30, v31
	ds_read2_b32 v[30:31], v32 offset0:198 offset1:231
	v_lshl_add_u64 v[42:43], s[6:7], 1, v[24:25]
	v_lshlrev_b64 v[40:41], 12, v[40:41]
	s_waitcnt lgkmcnt(0)
	v_cvt_pk_bf16_f32 v39, v30, v31
	ds_read2_b32 v[30:31], v32 offset0:8 offset1:41
	v_lshl_add_u64 v[40:41], v[42:43], 0, v[40:41]
	global_store_dwordx4 v[40:41], v[36:39], off
	v_or_b32_e32 v40, s2, v33
	v_ashrrev_i32_e32 v41, 31, v40
	s_waitcnt lgkmcnt(0)
	v_cvt_pk_bf16_f32 v36, v30, v31
	ds_read2_b32 v[30:31], v32 offset0:74 offset1:107
	s_waitcnt lgkmcnt(0)
	v_cvt_pk_bf16_f32 v37, v30, v31
	ds_read2_b32 v[30:31], v32 offset0:140 offset1:173
	s_waitcnt lgkmcnt(0)
	v_cvt_pk_bf16_f32 v38, v30, v31
	ds_read2_b32 v[30:31], v32 offset0:206 offset1:239
	v_lshlrev_b64 v[40:41], 12, v[40:41]
	s_waitcnt lgkmcnt(0)
	v_cvt_pk_bf16_f32 v39, v30, v31
	ds_read2_b32 v[30:31], v32 offset0:16 offset1:49
	v_lshl_add_u64 v[40:41], v[42:43], 0, v[40:41]
	global_store_dwordx4 v[40:41], v[36:39], off
	v_or_b32_e32 v40, s2, v34
	v_ashrrev_i32_e32 v41, 31, v40
	s_waitcnt lgkmcnt(0)
	v_cvt_pk_bf16_f32 v36, v30, v31
	ds_read2_b32 v[30:31], v32 offset0:82 offset1:115
	s_waitcnt lgkmcnt(0)
	v_cvt_pk_bf16_f32 v37, v30, v31
	ds_read2_b32 v[30:31], v32 offset0:148 offset1:181
	s_waitcnt lgkmcnt(0)
	v_cvt_pk_bf16_f32 v38, v30, v31
	ds_read2_b32 v[30:31], v32 offset0:214 offset1:247
	v_lshlrev_b64 v[40:41], 12, v[40:41]
	s_waitcnt lgkmcnt(0)
	v_cvt_pk_bf16_f32 v39, v30, v31
	ds_read2_b32 v[30:31], v32 offset0:24 offset1:57
	v_lshl_add_u64 v[40:41], v[42:43], 0, v[40:41]
	global_store_dwordx4 v[40:41], v[36:39], off
	v_or_b32_e32 v40, s2, v35
	v_ashrrev_i32_e32 v41, 31, v40
	s_waitcnt lgkmcnt(0)
	v_cvt_pk_bf16_f32 v36, v30, v31
	ds_read2_b32 v[30:31], v32 offset0:90 offset1:123
	s_waitcnt lgkmcnt(0)
	v_cvt_pk_bf16_f32 v37, v30, v31
	ds_read2_b32 v[30:31], v32 offset0:156 offset1:189
	s_waitcnt lgkmcnt(0)
	v_cvt_pk_bf16_f32 v38, v30, v31
	ds_read2_b32 v[30:31], v32 offset0:222 offset1:255
	v_lshlrev_b64 v[40:41], 12, v[40:41]
	s_waitcnt lgkmcnt(0)
	v_cvt_pk_bf16_f32 v39, v30, v31
	v_lshl_add_u64 v[30:31], v[42:43], 0, v[40:41]
	global_store_dwordx4 v[30:31], v[36:39], off
	s_waitcnt lgkmcnt(0)
	s_mov_b32 s6, s14
	s_andn2_b64 vcc, exec, s[0:1]
	s_cbranch_vccnz .LBB0_335

.LBB0_649:
	s_lshl_b32 s18, s4, 1
	s_lshl_b32 s19, s5, 1
	v_or_b32_e32 v50, s18, v1
	v_or_b32_e32 v51, s19, v0
	s_add_i32 s20, s18, 4
	s_add_i32 s21, s19, 4
	s_add_i32 s22, s18, 8
	s_add_i32 s23, s19, 8
	s_add_i32 s24, s18, 12
	s_add_i32 s25, s19, 12
	s_add_i32 s26, s18, 16
	s_add_i32 s27, s19, 16
	s_add_i32 s28, s18, 20
	s_add_i32 s29, s19, 20
	s_add_i32 s30, s18, 24
	s_add_i32 s31, s19, 24
	s_add_i32 s18, s18, 28
	s_add_i32 s19, s19, 28
	v_add_u32_e32 v18, s2, v51
	v_or_b32_e32 v52, s20, v1
	v_or_b32_e32 v53, s21, v0
	v_or_b32_e32 v54, s22, v1
	v_or_b32_e32 v55, s23, v0
	v_or_b32_e32 v56, s24, v1
	v_or_b32_e32 v57, s25, v0
	v_or_b32_e32 v58, s26, v1
	v_or_b32_e32 v59, s27, v0
	v_or_b32_e32 v60, s28, v1
	v_or_b32_e32 v61, s29, v0
	v_or_b32_e32 v62, s30, v1
	v_or_b32_e32 v63, s31, v0
	v_or_b32_e32 v64, s18, v1
	v_or_b32_e32 v65, s19, v0
	s_waitcnt vmcnt(0)
	v_add_u32_e32 v20, s3, v50
	v_mad_i64_i32 v[18:19], s[18:19], v18, s7, v[12:13]
	v_add_u32_e32 v24, s3, v52
	v_add_u32_e32 v22, s2, v53
	v_add_u32_e32 v28, s3, v54
	v_add_u32_e32 v26, s2, v55
	v_add_u32_e32 v32, s3, v56
	v_add_u32_e32 v30, s2, v57
	v_add_u32_e32 v36, s3, v58
	v_add_u32_e32 v34, s2, v59
	v_add_u32_e32 v40, s3, v60
	v_add_u32_e32 v38, s2, v61
	v_add_u32_e32 v44, s3, v62
	v_add_u32_e32 v42, s2, v63
	v_add_u32_e32 v48, s3, v64
	v_add_u32_e32 v46, s2, v65
	v_mad_i64_i32 v[20:21], s[18:19], v20, s7, v[12:13]
	v_mad_i64_i32 v[22:23], s[18:19], v22, s7, v[12:13]
	v_mad_i64_i32 v[24:25], s[18:19], v24, s7, v[12:13]
	v_mad_i64_i32 v[26:27], s[18:19], v26, s7, v[12:13]
	v_mad_i64_i32 v[28:29], s[18:19], v28, s7, v[12:13]
	v_mad_i64_i32 v[30:31], s[18:19], v30, s7, v[12:13]
	v_mad_i64_i32 v[32:33], s[18:19], v32, s7, v[12:13]
	v_mad_i64_i32 v[34:35], s[18:19], v34, s7, v[12:13]
	v_mad_i64_i32 v[36:37], s[18:19], v36, s7, v[12:13]
	v_mad_i64_i32 v[38:39], s[18:19], v38, s7, v[12:13]
	v_mad_i64_i32 v[40:41], s[18:19], v40, s7, v[12:13]
	v_mad_i64_i32 v[42:43], s[18:19], v42, s7, v[12:13]
	v_mad_i64_i32 v[44:45], s[18:19], v44, s7, v[12:13]
	v_mad_i64_i32 v[46:47], s[18:19], v46, s7, v[12:13]
	v_mad_i64_i32 v[48:49], s[18:19], v48, s7, v[12:13]
	global_load_dword v66, v[18:19], off
	global_load_dword v67, v[20:21], off
	global_load_dword v68, v[22:23], off
	global_load_dword v69, v[24:25], off
	global_load_dword v70, v[26:27], off
	global_load_dword v71, v[28:29], off
	global_load_dword v72, v[30:31], off
	global_load_dword v73, v[32:33], off
	global_load_dword v74, v[34:35], off
	global_load_dword v75, v[36:37], off
	global_load_dword v76, v[38:39], off
	global_load_dword v77, v[40:41], off
	global_load_dword v78, v[42:43], off
	global_load_dword v79, v[44:45], off
	global_load_dword v80, v[46:47], off
	global_load_dword v81, v[48:49], off
	s_add_i32 s5, s5, 16
	s_add_i32 s4, s4, 16
	s_lshl_b32 s18, s4, 1
	s_lshl_b32 s19, s5, 1
	v_or_b32_e32 v132, s18, v1
	v_or_b32_e32 v133, s19, v0
	s_add_i32 s20, s18, 4
	s_add_i32 s21, s19, 4
	s_add_i32 s22, s18, 8
	s_add_i32 s23, s19, 8
	s_add_i32 s24, s18, 12
	s_add_i32 s25, s19, 12
	s_add_i32 s26, s18, 16
	s_add_i32 s27, s19, 16
	s_add_i32 s28, s18, 20
	s_add_i32 s29, s19, 20
	s_add_i32 s30, s18, 24
	s_add_i32 s31, s19, 24
	s_add_i32 s18, s18, 28
	s_add_i32 s19, s19, 28
	v_add_u32_e32 v100, s2, v133
	v_or_b32_e32 v134, s20, v1
	v_or_b32_e32 v135, s21, v0
	v_or_b32_e32 v136, s22, v1
	v_or_b32_e32 v137, s23, v0
	v_or_b32_e32 v138, s24, v1
	v_or_b32_e32 v139, s25, v0
	v_or_b32_e32 v140, s26, v1
	v_or_b32_e32 v141, s27, v0
	v_or_b32_e32 v142, s28, v1
	v_or_b32_e32 v143, s29, v0
	v_or_b32_e32 v144, s30, v1
	v_or_b32_e32 v145, s31, v0
	v_or_b32_e32 v146, s18, v1
	v_or_b32_e32 v147, s19, v0
	v_add_u32_e32 v102, s3, v132
	v_mad_i64_i32 v[100:101], s[18:19], v100, s7, v[12:13]
	v_add_u32_e32 v106, s3, v134
	v_add_u32_e32 v104, s2, v135
	v_add_u32_e32 v110, s3, v136
	v_add_u32_e32 v108, s2, v137
	v_add_u32_e32 v114, s3, v138
	v_add_u32_e32 v112, s2, v139
	v_add_u32_e32 v118, s3, v140
	v_add_u32_e32 v116, s2, v141
	v_add_u32_e32 v122, s3, v142
	v_add_u32_e32 v120, s2, v143
	v_add_u32_e32 v126, s3, v144
	v_add_u32_e32 v124, s2, v145
	v_add_u32_e32 v130, s3, v146
	v_add_u32_e32 v128, s2, v147
	v_mad_i64_i32 v[102:103], s[18:19], v102, s7, v[12:13]
	v_mad_i64_i32 v[104:105], s[18:19], v104, s7, v[12:13]
	v_mad_i64_i32 v[106:107], s[18:19], v106, s7, v[12:13]
	v_mad_i64_i32 v[108:109], s[18:19], v108, s7, v[12:13]
	v_mad_i64_i32 v[110:111], s[18:19], v110, s7, v[12:13]
	v_mad_i64_i32 v[112:113], s[18:19], v112, s7, v[12:13]
	v_mad_i64_i32 v[114:115], s[18:19], v114, s7, v[12:13]
	v_mad_i64_i32 v[116:117], s[18:19], v116, s7, v[12:13]
	v_mad_i64_i32 v[118:119], s[18:19], v118, s7, v[12:13]
	v_mad_i64_i32 v[120:121], s[18:19], v120, s7, v[12:13]
	v_mad_i64_i32 v[122:123], s[18:19], v122, s7, v[12:13]
	v_mad_i64_i32 v[124:125], s[18:19], v124, s7, v[12:13]
	v_mad_i64_i32 v[126:127], s[18:19], v126, s7, v[12:13]
	v_mad_i64_i32 v[128:129], s[18:19], v128, s7, v[12:13]
	v_mad_i64_i32 v[130:131], s[18:19], v130, s7, v[12:13]
	global_load_dword v148, v[100:101], off
	global_load_dword v149, v[102:103], off
	global_load_dword v150, v[104:105], off
	global_load_dword v151, v[106:107], off
	global_load_dword v152, v[108:109], off
	global_load_dword v153, v[110:111], off
	global_load_dword v154, v[112:113], off
	global_load_dword v155, v[114:115], off
	global_load_dword v156, v[116:117], off
	global_load_dword v157, v[118:119], off
	global_load_dword v158, v[120:121], off
	global_load_dword v159, v[122:123], off
	global_load_dword v160, v[124:125], off
	global_load_dword v161, v[126:127], off
	global_load_dword v162, v[128:129], off
	global_load_dword v163, v[130:131], off
	v_mad_u64_u32 v[18:19], s[18:19], v51, s6, v[4:5]
	v_mad_u64_u32 v[20:21], s[18:19], v50, s6, v[4:5]
	v_mad_u64_u32 v[22:23], s[18:19], v53, s6, v[4:5]
	v_mad_u64_u32 v[24:25], s[18:19], v52, s6, v[4:5]
	v_mad_u64_u32 v[26:27], s[18:19], v55, s6, v[4:5]
	v_mad_u64_u32 v[28:29], s[18:19], v54, s6, v[4:5]
	v_mad_u64_u32 v[30:31], s[18:19], v57, s6, v[4:5]
	v_mad_u64_u32 v[32:33], s[18:19], v56, s6, v[4:5]
	v_mad_u64_u32 v[34:35], s[18:19], v59, s6, v[4:5]
	v_mad_u64_u32 v[36:37], s[18:19], v58, s6, v[4:5]
	v_mad_u64_u32 v[38:39], s[18:19], v61, s6, v[4:5]
	v_mad_u64_u32 v[40:41], s[18:19], v60, s6, v[4:5]
	v_mad_u64_u32 v[42:43], s[18:19], v63, s6, v[4:5]
	v_mad_u64_u32 v[44:45], s[18:19], v62, s6, v[4:5]
	v_mad_u64_u32 v[46:47], s[18:19], v65, s6, v[4:5]
	v_mad_u64_u32 v[48:49], s[18:19], v64, s6, v[4:5]
	s_waitcnt vmcnt(31)
	ds_write_b32 v18, v66
	s_waitcnt vmcnt(30)
	ds_write_b32 v20, v67
	s_waitcnt vmcnt(29)
	ds_write_b32 v22, v68
	s_waitcnt vmcnt(28)
	ds_write_b32 v24, v69
	s_waitcnt vmcnt(27)
	ds_write_b32 v26, v70
	s_waitcnt vmcnt(26)
	ds_write_b32 v28, v71
	s_waitcnt vmcnt(25)
	ds_write_b32 v30, v72
	s_waitcnt vmcnt(24)
	ds_write_b32 v32, v73
	s_waitcnt vmcnt(23)
	ds_write_b32 v34, v74
	s_waitcnt vmcnt(22)
	ds_write_b32 v36, v75
	s_waitcnt vmcnt(21)
	ds_write_b32 v38, v76
	s_waitcnt vmcnt(20)
	ds_write_b32 v40, v77
	s_waitcnt vmcnt(19)
	ds_write_b32 v42, v78
	s_waitcnt vmcnt(18)
	ds_write_b32 v44, v79
	s_waitcnt vmcnt(17)
	ds_write_b32 v46, v80
	s_waitcnt vmcnt(16)
	ds_write_b32 v48, v81
	v_mad_u64_u32 v[100:101], s[18:19], v133, s6, v[4:5]
	v_mad_u64_u32 v[102:103], s[18:19], v132, s6, v[4:5]
	v_mad_u64_u32 v[104:105], s[18:19], v135, s6, v[4:5]
	v_mad_u64_u32 v[106:107], s[18:19], v134, s6, v[4:5]
	v_mad_u64_u32 v[108:109], s[18:19], v137, s6, v[4:5]
	v_mad_u64_u32 v[110:111], s[18:19], v136, s6, v[4:5]
	v_mad_u64_u32 v[112:113], s[18:19], v139, s6, v[4:5]
	v_mad_u64_u32 v[114:115], s[18:19], v138, s6, v[4:5]
	v_mad_u64_u32 v[116:117], s[18:19], v141, s6, v[4:5]
	v_mad_u64_u32 v[118:119], s[18:19], v140, s6, v[4:5]
	v_mad_u64_u32 v[120:121], s[18:19], v143, s6, v[4:5]
	v_mad_u64_u32 v[122:123], s[18:19], v142, s6, v[4:5]
	v_mad_u64_u32 v[124:125], s[18:19], v145, s6, v[4:5]
	v_mad_u64_u32 v[126:127], s[18:19], v144, s6, v[4:5]
	v_mad_u64_u32 v[128:129], s[18:19], v147, s6, v[4:5]
	v_mad_u64_u32 v[130:131], s[18:19], v146, s6, v[4:5]
	s_waitcnt vmcnt(15)
	ds_write_b32 v100, v148
	s_waitcnt vmcnt(14)
	ds_write_b32 v102, v149
	s_waitcnt vmcnt(13)
	ds_write_b32 v104, v150
	s_waitcnt vmcnt(12)
	ds_write_b32 v106, v151
	s_waitcnt vmcnt(11)
	ds_write_b32 v108, v152
	s_waitcnt vmcnt(10)
	ds_write_b32 v110, v153
	s_waitcnt vmcnt(9)
	ds_write_b32 v112, v154
	s_waitcnt vmcnt(8)
	ds_write_b32 v114, v155
	s_waitcnt vmcnt(7)
	ds_write_b32 v116, v156
	s_waitcnt vmcnt(6)
	ds_write_b32 v118, v157
	s_waitcnt vmcnt(5)
	ds_write_b32 v120, v158
	s_waitcnt vmcnt(4)
	ds_write_b32 v122, v159
	s_waitcnt vmcnt(3)
	ds_write_b32 v124, v160
	s_waitcnt vmcnt(2)
	ds_write_b32 v126, v161
	s_waitcnt vmcnt(1)
	ds_write_b32 v128, v162
	s_waitcnt vmcnt(0)
	ds_write_b32 v130, v163
	s_add_i32 s5, s5, 16
	s_add_i32 s4, s4, 16
	s_add_i32 s15, s15, -16
	s_add_i32 s15, s15, -16
	s_cmp_lg_u32 s15, 0
	s_waitcnt lgkmcnt(0)
	ds_read2_b32 v[12:13], v14 offset1:33
	s_waitcnt lgkmcnt(0)
	v_cvt_pk_bf16_f32 v18, v12, v13
	ds_read2_b32 v[12:13], v14 offset0:66 offset1:99
	v_add_u32_e32 v22, s14, v5
	s_waitcnt lgkmcnt(0)
	v_cvt_pk_bf16_f32 v19, v12, v13
	ds_read2_b32 v[12:13], v14 offset0:132 offset1:165
	s_ashr_i32 s3, s2, 31
	v_ashrrev_i32_e32 v23, 31, v22
	s_waitcnt lgkmcnt(0)
	v_cvt_pk_bf16_f32 v20, v12, v13
	ds_read2_b32 v[12:13], v14 offset0:198 offset1:231
	v_lshl_add_u64 v[24:25], s[2:3], 1, v[6:7]
	v_lshlrev_b64 v[22:23], 12, v[22:23]
	s_waitcnt lgkmcnt(0)
	v_cvt_pk_bf16_f32 v21, v12, v13
	ds_read2_b32 v[12:13], v14 offset0:8 offset1:41
	v_lshl_add_u64 v[22:23], v[24:25], 0, v[22:23]
	global_store_dwordx4 v[22:23], v[18:21], off
	v_add_u32_e32 v22, s14, v15
	v_ashrrev_i32_e32 v23, 31, v22
	s_waitcnt lgkmcnt(0)
	v_cvt_pk_bf16_f32 v18, v12, v13
	ds_read2_b32 v[12:13], v14 offset0:74 offset1:107
	s_waitcnt lgkmcnt(0)
	v_cvt_pk_bf16_f32 v19, v12, v13
	ds_read2_b32 v[12:13], v14 offset0:140 offset1:173
	s_waitcnt lgkmcnt(0)
	v_cvt_pk_bf16_f32 v20, v12, v13
	ds_read2_b32 v[12:13], v14 offset0:206 offset1:239
	v_lshlrev_b64 v[22:23], 12, v[22:23]
	s_waitcnt lgkmcnt(0)
	v_cvt_pk_bf16_f32 v21, v12, v13
	ds_read2_b32 v[12:13], v14 offset0:16 offset1:49
	v_lshl_add_u64 v[22:23], v[24:25], 0, v[22:23]
	global_store_dwordx4 v[22:23], v[18:21], off
	v_add_u32_e32 v22, s14, v16
	v_ashrrev_i32_e32 v23, 31, v22
	s_waitcnt lgkmcnt(0)
	v_cvt_pk_bf16_f32 v18, v12, v13
	ds_read2_b32 v[12:13], v14 offset0:82 offset1:115
	s_waitcnt lgkmcnt(0)
	v_cvt_pk_bf16_f32 v19, v12, v13
	ds_read2_b32 v[12:13], v14 offset0:148 offset1:181
	s_waitcnt lgkmcnt(0)
	v_cvt_pk_bf16_f32 v20, v12, v13
	ds_read2_b32 v[12:13], v14 offset0:214 offset1:247
	v_lshlrev_b64 v[22:23], 12, v[22:23]
	s_waitcnt lgkmcnt(0)
	v_cvt_pk_bf16_f32 v21, v12, v13
	ds_read2_b32 v[12:13], v14 offset0:24 offset1:57
	v_lshl_add_u64 v[22:23], v[24:25], 0, v[22:23]
	global_store_dwordx4 v[22:23], v[18:21], off
	v_add_u32_e32 v22, s14, v17
	v_ashrrev_i32_e32 v23, 31, v22
	s_waitcnt lgkmcnt(0)
	v_cvt_pk_bf16_f32 v18, v12, v13
	ds_read2_b32 v[12:13], v14 offset0:90 offset1:123
	s_waitcnt lgkmcnt(0)
	v_cvt_pk_bf16_f32 v19, v12, v13
	ds_read2_b32 v[12:13], v14 offset0:156 offset1:189
	s_waitcnt lgkmcnt(0)
	v_cvt_pk_bf16_f32 v20, v12, v13
	ds_read2_b32 v[12:13], v14 offset0:222 offset1:255
	v_lshlrev_b64 v[22:23], 12, v[22:23]
	s_waitcnt lgkmcnt(0)
	v_cvt_pk_bf16_f32 v21, v12, v13
	v_lshl_add_u64 v[12:13], v[24:25], 0, v[22:23]
	global_store_dwordx4 v[12:13], v[18:21], off
	s_waitcnt lgkmcnt(0)
	s_mov_b64 s[2:3], 0

.LBB0_655:
	s_lshl_b32 s14, s3, 1
	s_lshl_b32 s15, s4, 1
	v_or_b32_e32 v50, s14, v1
	v_or_b32_e32 v51, s15, v0
	s_add_i32 s18, s14, 4
	s_add_i32 s19, s15, 4
	s_add_i32 s20, s14, 8
	s_add_i32 s21, s15, 8
	s_add_i32 s22, s14, 12
	s_add_i32 s23, s15, 12
	s_add_i32 s24, s14, 16
	s_add_i32 s25, s15, 16
	s_add_i32 s26, s14, 20
	s_add_i32 s27, s15, 20
	s_add_i32 s28, s14, 24
	s_add_i32 s29, s15, 24
	s_add_i32 s14, s14, 28
	s_add_i32 s15, s15, 28
	s_waitcnt vmcnt(0)
	v_add_u32_e32 v20, s2, v51
	v_or_b32_e32 v52, s18, v1
	v_or_b32_e32 v53, s19, v0
	v_or_b32_e32 v54, s20, v1
	v_or_b32_e32 v55, s21, v0
	v_or_b32_e32 v56, s22, v1
	v_or_b32_e32 v57, s23, v0
	v_or_b32_e32 v58, s24, v1
	v_or_b32_e32 v59, s25, v0
	v_or_b32_e32 v60, s26, v1
	v_or_b32_e32 v61, s27, v0
	v_or_b32_e32 v62, s28, v1
	v_or_b32_e32 v63, s29, v0
	v_or_b32_e32 v64, s14, v1
	v_or_b32_e32 v65, s15, v0
	v_add_u32_e32 v18, s1, v50
	v_ashrrev_i32_e32 v21, 31, v20
	v_add_u32_e32 v22, s1, v52
	v_add_u32_e32 v24, s2, v53
	v_add_u32_e32 v26, s1, v54
	v_add_u32_e32 v28, s2, v55
	v_add_u32_e32 v30, s1, v56
	v_add_u32_e32 v32, s2, v57
	v_add_u32_e32 v34, s1, v58
	v_add_u32_e32 v36, s2, v59
	v_add_u32_e32 v38, s1, v60
	v_add_u32_e32 v40, s2, v61
	v_add_u32_e32 v42, s1, v62
	v_add_u32_e32 v44, s2, v63
	v_add_u32_e32 v46, s1, v64
	v_add_u32_e32 v48, s2, v65
	v_ashrrev_i32_e32 v19, 31, v18
	v_lshlrev_b64 v[20:21], 13, v[20:21]
	v_ashrrev_i32_e32 v25, 31, v24
	v_ashrrev_i32_e32 v23, 31, v22
	v_ashrrev_i32_e32 v29, 31, v28
	v_ashrrev_i32_e32 v27, 31, v26
	v_ashrrev_i32_e32 v33, 31, v32
	v_ashrrev_i32_e32 v31, 31, v30
	v_ashrrev_i32_e32 v37, 31, v36
	v_ashrrev_i32_e32 v35, 31, v34
	v_ashrrev_i32_e32 v41, 31, v40
	v_ashrrev_i32_e32 v39, 31, v38
	v_ashrrev_i32_e32 v45, 31, v44
	v_ashrrev_i32_e32 v43, 31, v42
	v_ashrrev_i32_e32 v49, 31, v48
	v_ashrrev_i32_e32 v47, 31, v46
	v_lshlrev_b64 v[18:19], 13, v[18:19]
	v_lshl_add_u64 v[20:21], v[12:13], 0, v[20:21]
	v_lshlrev_b64 v[22:23], 13, v[22:23]
	v_lshlrev_b64 v[24:25], 13, v[24:25]
	v_lshlrev_b64 v[26:27], 13, v[26:27]
	v_lshlrev_b64 v[28:29], 13, v[28:29]
	v_lshlrev_b64 v[30:31], 13, v[30:31]
	v_lshlrev_b64 v[32:33], 13, v[32:33]
	v_lshlrev_b64 v[34:35], 13, v[34:35]
	v_lshlrev_b64 v[36:37], 13, v[36:37]
	v_lshlrev_b64 v[38:39], 13, v[38:39]
	v_lshlrev_b64 v[40:41], 13, v[40:41]
	v_lshlrev_b64 v[42:43], 13, v[42:43]
	v_lshlrev_b64 v[44:45], 13, v[44:45]
	v_lshlrev_b64 v[46:47], 13, v[46:47]
	v_lshlrev_b64 v[48:49], 13, v[48:49]
	v_lshl_add_u64 v[18:19], v[12:13], 0, v[18:19]
	v_lshl_add_u64 v[24:25], v[12:13], 0, v[24:25]
	v_lshl_add_u64 v[22:23], v[12:13], 0, v[22:23]
	v_lshl_add_u64 v[28:29], v[12:13], 0, v[28:29]
	v_lshl_add_u64 v[26:27], v[12:13], 0, v[26:27]
	v_lshl_add_u64 v[32:33], v[12:13], 0, v[32:33]
	v_lshl_add_u64 v[30:31], v[12:13], 0, v[30:31]
	v_lshl_add_u64 v[36:37], v[12:13], 0, v[36:37]
	v_lshl_add_u64 v[34:35], v[12:13], 0, v[34:35]
	v_lshl_add_u64 v[40:41], v[12:13], 0, v[40:41]
	v_lshl_add_u64 v[38:39], v[12:13], 0, v[38:39]
	v_lshl_add_u64 v[44:45], v[12:13], 0, v[44:45]
	v_lshl_add_u64 v[42:43], v[12:13], 0, v[42:43]
	v_lshl_add_u64 v[48:49], v[12:13], 0, v[48:49]
	v_lshl_add_u64 v[46:47], v[12:13], 0, v[46:47]
	global_load_dword v66, v[20:21], off
	global_load_dword v67, v[18:19], off
	global_load_dword v68, v[24:25], off
	global_load_dword v69, v[22:23], off
	global_load_dword v70, v[28:29], off
	global_load_dword v71, v[26:27], off
	global_load_dword v72, v[32:33], off
	global_load_dword v73, v[30:31], off
	global_load_dword v74, v[36:37], off
	global_load_dword v75, v[34:35], off
	global_load_dword v76, v[40:41], off
	global_load_dword v77, v[38:39], off
	global_load_dword v78, v[44:45], off
	global_load_dword v79, v[42:43], off
	global_load_dword v80, v[48:49], off
	global_load_dword v81, v[46:47], off
	s_add_i32 s4, s4, 16
	s_add_i32 s3, s3, 16
	s_lshl_b32 s14, s3, 1
	s_lshl_b32 s15, s4, 1
	v_or_b32_e32 v132, s14, v1
	v_or_b32_e32 v133, s15, v0
	s_add_i32 s18, s14, 4
	s_add_i32 s19, s15, 4
	s_add_i32 s20, s14, 8
	s_add_i32 s21, s15, 8
	s_add_i32 s22, s14, 12
	s_add_i32 s23, s15, 12
	s_add_i32 s24, s14, 16
	s_add_i32 s25, s15, 16
	s_add_i32 s26, s14, 20
	s_add_i32 s27, s15, 20
	s_add_i32 s28, s14, 24
	s_add_i32 s29, s15, 24
	s_add_i32 s14, s14, 28
	s_add_i32 s15, s15, 28
	v_add_u32_e32 v102, s2, v133
	v_or_b32_e32 v134, s18, v1
	v_or_b32_e32 v135, s19, v0
	v_or_b32_e32 v136, s20, v1
	v_or_b32_e32 v137, s21, v0
	v_or_b32_e32 v138, s22, v1
	v_or_b32_e32 v139, s23, v0
	v_or_b32_e32 v140, s24, v1
	v_or_b32_e32 v141, s25, v0
	v_or_b32_e32 v142, s26, v1
	v_or_b32_e32 v143, s27, v0
	v_or_b32_e32 v144, s28, v1
	v_or_b32_e32 v145, s29, v0
	v_or_b32_e32 v146, s14, v1
	v_or_b32_e32 v147, s15, v0
	v_add_u32_e32 v100, s1, v132
	v_ashrrev_i32_e32 v103, 31, v102
	v_add_u32_e32 v104, s1, v134
	v_add_u32_e32 v106, s2, v135
	v_add_u32_e32 v108, s1, v136
	v_add_u32_e32 v110, s2, v137
	v_add_u32_e32 v112, s1, v138
	v_add_u32_e32 v114, s2, v139
	v_add_u32_e32 v116, s1, v140
	v_add_u32_e32 v118, s2, v141
	v_add_u32_e32 v120, s1, v142
	v_add_u32_e32 v122, s2, v143
	v_add_u32_e32 v124, s1, v144
	v_add_u32_e32 v126, s2, v145
	v_add_u32_e32 v128, s1, v146
	v_add_u32_e32 v130, s2, v147
	v_ashrrev_i32_e32 v101, 31, v100
	v_lshlrev_b64 v[102:103], 13, v[102:103]
	v_ashrrev_i32_e32 v107, 31, v106
	v_ashrrev_i32_e32 v105, 31, v104
	v_ashrrev_i32_e32 v111, 31, v110
	v_ashrrev_i32_e32 v109, 31, v108
	v_ashrrev_i32_e32 v115, 31, v114
	v_ashrrev_i32_e32 v113, 31, v112
	v_ashrrev_i32_e32 v119, 31, v118
	v_ashrrev_i32_e32 v117, 31, v116
	v_ashrrev_i32_e32 v123, 31, v122
	v_ashrrev_i32_e32 v121, 31, v120
	v_ashrrev_i32_e32 v127, 31, v126
	v_ashrrev_i32_e32 v125, 31, v124
	v_ashrrev_i32_e32 v131, 31, v130
	v_ashrrev_i32_e32 v129, 31, v128
	v_lshlrev_b64 v[100:101], 13, v[100:101]
	v_lshl_add_u64 v[102:103], v[12:13], 0, v[102:103]
	v_lshlrev_b64 v[104:105], 13, v[104:105]
	v_lshlrev_b64 v[106:107], 13, v[106:107]
	v_lshlrev_b64 v[108:109], 13, v[108:109]
	v_lshlrev_b64 v[110:111], 13, v[110:111]
	v_lshlrev_b64 v[112:113], 13, v[112:113]
	v_lshlrev_b64 v[114:115], 13, v[114:115]
	v_lshlrev_b64 v[116:117], 13, v[116:117]
	v_lshlrev_b64 v[118:119], 13, v[118:119]
	v_lshlrev_b64 v[120:121], 13, v[120:121]
	v_lshlrev_b64 v[122:123], 13, v[122:123]
	v_lshlrev_b64 v[124:125], 13, v[124:125]
	v_lshlrev_b64 v[126:127], 13, v[126:127]
	v_lshlrev_b64 v[128:129], 13, v[128:129]
	v_lshlrev_b64 v[130:131], 13, v[130:131]
	v_lshl_add_u64 v[100:101], v[12:13], 0, v[100:101]
	v_lshl_add_u64 v[106:107], v[12:13], 0, v[106:107]
	v_lshl_add_u64 v[104:105], v[12:13], 0, v[104:105]
	v_lshl_add_u64 v[110:111], v[12:13], 0, v[110:111]
	v_lshl_add_u64 v[108:109], v[12:13], 0, v[108:109]
	v_lshl_add_u64 v[114:115], v[12:13], 0, v[114:115]
	v_lshl_add_u64 v[112:113], v[12:13], 0, v[112:113]
	v_lshl_add_u64 v[118:119], v[12:13], 0, v[118:119]
	v_lshl_add_u64 v[116:117], v[12:13], 0, v[116:117]
	v_lshl_add_u64 v[122:123], v[12:13], 0, v[122:123]
	v_lshl_add_u64 v[120:121], v[12:13], 0, v[120:121]
	v_lshl_add_u64 v[126:127], v[12:13], 0, v[126:127]
	v_lshl_add_u64 v[124:125], v[12:13], 0, v[124:125]
	v_lshl_add_u64 v[130:131], v[12:13], 0, v[130:131]
	v_lshl_add_u64 v[128:129], v[12:13], 0, v[128:129]
	global_load_dword v148, v[102:103], off
	global_load_dword v149, v[100:101], off
	global_load_dword v150, v[106:107], off
	global_load_dword v151, v[104:105], off
	global_load_dword v152, v[110:111], off
	global_load_dword v153, v[108:109], off
	global_load_dword v154, v[114:115], off
	global_load_dword v155, v[112:113], off
	global_load_dword v156, v[118:119], off
	global_load_dword v157, v[116:117], off
	global_load_dword v158, v[122:123], off
	global_load_dword v159, v[120:121], off
	global_load_dword v160, v[126:127], off
	global_load_dword v161, v[124:125], off
	global_load_dword v162, v[130:131], off
	global_load_dword v163, v[128:129], off
	v_mad_u64_u32 v[18:19], s[14:15], v51, s6, v[4:5]
	v_mad_u64_u32 v[20:21], s[14:15], v50, s6, v[4:5]
	v_mad_u64_u32 v[22:23], s[14:15], v53, s6, v[4:5]
	v_mad_u64_u32 v[24:25], s[14:15], v52, s6, v[4:5]
	v_mad_u64_u32 v[26:27], s[14:15], v55, s6, v[4:5]
	v_mad_u64_u32 v[28:29], s[14:15], v54, s6, v[4:5]
	v_mad_u64_u32 v[30:31], s[14:15], v57, s6, v[4:5]
	v_mad_u64_u32 v[32:33], s[14:15], v56, s6, v[4:5]
	v_mad_u64_u32 v[34:35], s[14:15], v59, s6, v[4:5]
	v_mad_u64_u32 v[36:37], s[14:15], v58, s6, v[4:5]
	v_mad_u64_u32 v[38:39], s[14:15], v61, s6, v[4:5]
	v_mad_u64_u32 v[40:41], s[14:15], v60, s6, v[4:5]
	v_mad_u64_u32 v[42:43], s[14:15], v63, s6, v[4:5]
	v_mad_u64_u32 v[44:45], s[14:15], v62, s6, v[4:5]
	v_mad_u64_u32 v[46:47], s[14:15], v65, s6, v[4:5]
	v_mad_u64_u32 v[48:49], s[14:15], v64, s6, v[4:5]
	s_waitcnt vmcnt(31)
	ds_write_b32 v18, v66
	s_waitcnt vmcnt(30)
	ds_write_b32 v20, v67
	s_waitcnt vmcnt(29)
	ds_write_b32 v22, v68
	s_waitcnt vmcnt(28)
	ds_write_b32 v24, v69
	s_waitcnt vmcnt(27)
	ds_write_b32 v26, v70
	s_waitcnt vmcnt(26)
	ds_write_b32 v28, v71
	s_waitcnt vmcnt(25)
	ds_write_b32 v30, v72
	s_waitcnt vmcnt(24)
	ds_write_b32 v32, v73
	s_waitcnt vmcnt(23)
	ds_write_b32 v34, v74
	s_waitcnt vmcnt(22)
	ds_write_b32 v36, v75
	s_waitcnt vmcnt(21)
	ds_write_b32 v38, v76
	s_waitcnt vmcnt(20)
	ds_write_b32 v40, v77
	s_waitcnt vmcnt(19)
	ds_write_b32 v42, v78
	s_waitcnt vmcnt(18)
	ds_write_b32 v44, v79
	s_waitcnt vmcnt(17)
	ds_write_b32 v46, v80
	s_waitcnt vmcnt(16)
	ds_write_b32 v48, v81
	v_mad_u64_u32 v[100:101], s[14:15], v133, s6, v[4:5]
	v_mad_u64_u32 v[102:103], s[14:15], v132, s6, v[4:5]
	v_mad_u64_u32 v[104:105], s[14:15], v135, s6, v[4:5]
	v_mad_u64_u32 v[106:107], s[14:15], v134, s6, v[4:5]
	v_mad_u64_u32 v[108:109], s[14:15], v137, s6, v[4:5]
	v_mad_u64_u32 v[110:111], s[14:15], v136, s6, v[4:5]
	v_mad_u64_u32 v[112:113], s[14:15], v139, s6, v[4:5]
	v_mad_u64_u32 v[114:115], s[14:15], v138, s6, v[4:5]
	v_mad_u64_u32 v[116:117], s[14:15], v141, s6, v[4:5]
	v_mad_u64_u32 v[118:119], s[14:15], v140, s6, v[4:5]
	v_mad_u64_u32 v[120:121], s[14:15], v143, s6, v[4:5]
	v_mad_u64_u32 v[122:123], s[14:15], v142, s6, v[4:5]
	v_mad_u64_u32 v[124:125], s[14:15], v145, s6, v[4:5]
	v_mad_u64_u32 v[126:127], s[14:15], v144, s6, v[4:5]
	v_mad_u64_u32 v[128:129], s[14:15], v147, s6, v[4:5]
	v_mad_u64_u32 v[130:131], s[14:15], v146, s6, v[4:5]
	s_waitcnt vmcnt(15)
	ds_write_b32 v100, v148
	s_waitcnt vmcnt(14)
	ds_write_b32 v102, v149
	s_waitcnt vmcnt(13)
	ds_write_b32 v104, v150
	s_waitcnt vmcnt(12)
	ds_write_b32 v106, v151
	s_waitcnt vmcnt(11)
	ds_write_b32 v108, v152
	s_waitcnt vmcnt(10)
	ds_write_b32 v110, v153
	s_waitcnt vmcnt(9)
	ds_write_b32 v112, v154
	s_waitcnt vmcnt(8)
	ds_write_b32 v114, v155
	s_waitcnt vmcnt(7)
	ds_write_b32 v116, v156
	s_waitcnt vmcnt(6)
	ds_write_b32 v118, v157
	s_waitcnt vmcnt(5)
	ds_write_b32 v120, v158
	s_waitcnt vmcnt(4)
	ds_write_b32 v122, v159
	s_waitcnt vmcnt(3)
	ds_write_b32 v124, v160
	s_waitcnt vmcnt(2)
	ds_write_b32 v126, v161
	s_waitcnt vmcnt(1)
	ds_write_b32 v128, v162
	s_waitcnt vmcnt(0)
	ds_write_b32 v130, v163
	s_add_i32 s4, s4, 16
	s_add_i32 s3, s3, 16
	s_add_i32 s5, s5, -16
	s_add_i32 s5, s5, -16
	s_cmp_lg_u32 s5, 0
	s_waitcnt lgkmcnt(0)
	ds_read2_b32 v[12:13], v14 offset1:33
	s_waitcnt lgkmcnt(0)
	v_cvt_pk_bf16_f32 v18, v12, v13
	ds_read2_b32 v[12:13], v14 offset0:66 offset1:99
	v_or_b32_e32 v24, s0, v5
	s_waitcnt lgkmcnt(0)
	v_cvt_pk_bf16_f32 v19, v12, v13
	ds_read2_b32 v[12:13], v14 offset0:132 offset1:165
	s_ashr_i32 s3, s2, 31
	v_mul_lo_u32 v24, v24, s8
	s_waitcnt lgkmcnt(0)
	v_cvt_pk_bf16_f32 v20, v12, v13
	ds_read2_b32 v[12:13], v14 offset0:198 offset1:231
	v_lshl_add_u64 v[22:23], s[2:3], 1, v[10:11]
	v_ashrrev_i32_e32 v25, 31, v24
	s_waitcnt lgkmcnt(0)
	v_cvt_pk_bf16_f32 v21, v12, v13
	ds_read2_b32 v[12:13], v14 offset0:8 offset1:41
	v_lshl_add_u64 v[24:25], v[24:25], 1, v[22:23]
	global_store_dwordx4 v[24:25], v[18:21], off
	v_or_b32_e32 v24, s0, v15
	v_mul_lo_u32 v24, v24, s8
	s_waitcnt lgkmcnt(0)
	v_cvt_pk_bf16_f32 v18, v12, v13
	ds_read2_b32 v[12:13], v14 offset0:74 offset1:107
	s_waitcnt lgkmcnt(0)
	v_cvt_pk_bf16_f32 v19, v12, v13
	ds_read2_b32 v[12:13], v14 offset0:140 offset1:173
	s_waitcnt lgkmcnt(0)
	v_cvt_pk_bf16_f32 v20, v12, v13
	ds_read2_b32 v[12:13], v14 offset0:206 offset1:239
	v_ashrrev_i32_e32 v25, 31, v24
	s_waitcnt lgkmcnt(0)
	v_cvt_pk_bf16_f32 v21, v12, v13
	ds_read2_b32 v[12:13], v14 offset0:16 offset1:49
	v_lshl_add_u64 v[24:25], v[24:25], 1, v[22:23]
	global_store_dwordx4 v[24:25], v[18:21], off
	v_or_b32_e32 v24, s0, v16
	v_mul_lo_u32 v24, v24, s8
	s_waitcnt lgkmcnt(0)
	v_cvt_pk_bf16_f32 v18, v12, v13
	ds_read2_b32 v[12:13], v14 offset0:82 offset1:115
	s_waitcnt lgkmcnt(0)
	v_cvt_pk_bf16_f32 v19, v12, v13
	ds_read2_b32 v[12:13], v14 offset0:148 offset1:181
	s_waitcnt lgkmcnt(0)
	v_cvt_pk_bf16_f32 v20, v12, v13
	ds_read2_b32 v[12:13], v14 offset0:214 offset1:247
	v_ashrrev_i32_e32 v25, 31, v24
	s_waitcnt lgkmcnt(0)
	v_cvt_pk_bf16_f32 v21, v12, v13
	ds_read2_b32 v[12:13], v14 offset0:24 offset1:57
	v_lshl_add_u64 v[24:25], v[24:25], 1, v[22:23]
	global_store_dwordx4 v[24:25], v[18:21], off
	s_waitcnt lgkmcnt(0)
	s_nop 0
	v_cvt_pk_bf16_f32 v18, v12, v13
	ds_read2_b32 v[12:13], v14 offset0:90 offset1:123
	v_or_b32_e32 v21, s0, v17
	s_waitcnt lgkmcnt(0)
	v_cvt_pk_bf16_f32 v19, v12, v13
	ds_read2_b32 v[12:13], v14 offset0:156 offset1:189
	v_mul_lo_u32 v24, v21, s8
	s_waitcnt lgkmcnt(0)
	v_cvt_pk_bf16_f32 v20, v12, v13
	ds_read2_b32 v[12:13], v14 offset0:222 offset1:255
	v_ashrrev_i32_e32 v25, 31, v24
	s_waitcnt lgkmcnt(0)
	v_cvt_pk_bf16_f32 v21, v12, v13
	v_lshl_add_u64 v[12:13], v[24:25], 1, v[22:23]
	global_store_dwordx4 v[12:13], v[18:21], off
	s_waitcnt lgkmcnt(0)
	s_branch .LBB0_642
